# gate-up phases: epilogue no longer waits for the next tile's prefetch DMAs up front (single vmcnt(7) before its last store)
# baseline (speedup 1.0000x reference)
; #define PG8_STAGE(bufoff, gbase, voff) do { _Pragma("unroll") for (int _i = 0; _i < 2; ++_i) \
;         __builtin_amdgcn_global_load_lds((const unsigned*)((const char*)(gbase) + (voff)[_i]), (LAS unsigned*)(lds + (bufoff) + ldsw + _i * 8192), 16, 0, 0); } while (0)
; #define PG8_LDA(dst, b, h) do { _Pragma("unroll") for (int m = 0; m < 4; ++m) _Pragma("unroll") for (int k = 0; k < 2; ++k) dst[m][k] = *(const LAS bf16x8*)(lds + PG8_SA(b, h) + aoff + m * 2048 + k * 1024); } while (0)
; #define PG8_LDB(dst, b, h) do { _Pragma("unroll") for (int n = 0; n < 2; ++n) _Pragma("unroll") for (int k = 0; k < 2; ++k) dst[n][k] = *(const LAS bf16x8*)(lds + PG8_SB(b, h) + boff + n * 2048 + k * 1024); } while (0)
; #define PG8_MMA(ai, bj, At, Bt) do { __builtin_amdgcn_s_setprio(1); _Pragma("unroll") for (int m = 0; m < 4; ++m) _Pragma("unroll") for (int n = 0; n < 2; ++n) _Pragma("unroll") for (int k = 0; k < 2; ++k) \
;         acc[ai][bj][m][n] = __builtin_amdgcn_mfma_f32_16x16x32_bf16(Bt[n][k], At[m][k], acc[ai][bj][m][n], 0, 0, 0); __builtin_amdgcn_s_setprio(0); } while (0)
; #define PG8_WAIT_V(n) asm volatile("s_waitcnt vmcnt(" #n ")" ::: "memory")
; #define PG8_WAIT_L(n) asm volatile("s_waitcnt lgkmcnt(" #n ")" ::: "memory")
; #define PG8_BAR __builtin_amdgcn_s_barrier()
; #define PG8_SCHED __builtin_amdgcn_sched_barrier(0)
; template <class Epi, class Sched>
; DI void gemm_phase(LAS unsigned char* lds, const Gemm g, const Sched& S, const Epi& E) {
;     ...
;             PG8_LDB(B0, 0, 0); PG8_LDB(B1, 0, 1); PG8_SCHED; PG8_LDA(At, 0, 0); PG8_STAGE(PG8_SA(1, 1), a1 + hstepA, voffA);
;             PG8_WAIT_V(8); PG8_WAIT_L(0); PG8_BAR; PG8_MMA(0, 0, At, B0); PG8_MMA(0, 1, At, B1); PG8_BAR; PG8_SCHED;
;             PG8_LDA(At, 0, 1); PG8_STAGE(PG8_SB(0, 0), b2, voffB); PG8_STAGE(PG8_SB(0, 1), b2 + hstepB, voffB); PG8_STAGE(PG8_SA(0, 0), a2, voffA);
;             PG8_WAIT_V(8); PG8_WAIT_L(0); PG8_BAR; PG8_MMA(1, 0, At, B0); PG8_MMA(1, 1, At, B1); PG8_BAR; PG8_SCHED;
.LBB0_179:
	ds_read_b128 v[168:171], v162
	ds_read_b128 v[172:175], v162 offset:1024
	ds_read_b128 v[176:179], v162 offset:2048
	ds_read_b128 v[180:183], v162 offset:3072
	ds_read_b128 v[186:189], v163
	ds_read_b128 v[190:193], v163 offset:1024
	ds_read_b128 v[194:197], v163 offset:2048
	ds_read_b128 v[198:201], v163 offset:3072
	s_add_u32 s42, s40, 0xfffc0080
	s_addc_u32 s43, s41, -1
	s_cmp_eq_u32 s65, 12
	s_cselect_b32 s45, s35, s43
	s_cselect_b32 s44, s61, s42
	s_cselect_b32 s43, s21, s64
	s_cselect_b32 s42, s62, s63
	v_lshl_add_u64 v[234:235], s[40:41], 0, v[138:139]
	s_add_i32 m0, s49, 0xc000
	ds_read_b128 v[202:205], v160
	ds_read_b128 v[206:209], v160 offset:1024
	ds_read_b128 v[210:213], v160 offset:2048
	ds_read_b128 v[214:217], v160 offset:3072
	ds_read_b128 v[218:221], v160 offset:4096
	ds_read_b128 v[222:225], v160 offset:5120
	ds_read_b128 v[226:229], v160 offset:6144
	ds_read_b128 v[230:233], v160 offset:7168
	global_load_lds_dwordx4 v[234:235], off
	v_lshl_add_u64 v[234:235], s[40:41], 0, v[140:141]
	s_add_i32 m0, s49, 0xe000
	s_nop 0
	global_load_lds_dwordx4 v[234:235], off
	s_waitcnt vmcnt(8)
	s_waitcnt lgkmcnt(0)
	s_barrier
	s_setprio 1
	v_mfma_f32_16x16x32_bf16 v[126:129], v[168:171], v[202:205], v[126:129]
	v_mfma_f32_16x16x32_bf16 v[118:121], v[176:179], v[202:205], v[118:121]
	v_mfma_f32_16x16x32_bf16 v[110:113], v[168:171], v[210:213], v[110:113]
	v_mfma_f32_16x16x32_bf16 v[102:105], v[176:179], v[210:213], v[102:105]
	v_mfma_f32_16x16x32_bf16 v[94:97], v[168:171], v[218:221], v[94:97]
	v_mfma_f32_16x16x32_bf16 v[86:89], v[176:179], v[218:221], v[86:89]
	v_mfma_f32_16x16x32_bf16 v[78:81], v[168:171], v[226:229], v[78:81]
	v_mfma_f32_16x16x32_bf16 v[70:73], v[176:179], v[226:229], v[70:73]
	v_mfma_f32_16x16x32_bf16 v[126:129], v[172:175], v[206:209], v[126:129]
	v_mfma_f32_16x16x32_bf16 v[118:121], v[180:183], v[206:209], v[118:121]
	v_mfma_f32_16x16x32_bf16 v[110:113], v[172:175], v[214:217], v[110:113]
	v_mfma_f32_16x16x32_bf16 v[102:105], v[180:183], v[214:217], v[102:105]
	v_mfma_f32_16x16x32_bf16 v[94:97], v[172:175], v[222:225], v[94:97]
	v_mfma_f32_16x16x32_bf16 v[86:89], v[180:183], v[222:225], v[86:89]
	v_mfma_f32_16x16x32_bf16 v[78:81], v[172:175], v[230:233], v[78:81]
	v_mfma_f32_16x16x32_bf16 v[70:73], v[180:183], v[230:233], v[70:73]
	v_mfma_f32_16x16x32_bf16 v[122:125], v[186:189], v[202:205], v[122:125]
	v_mfma_f32_16x16x32_bf16 v[114:117], v[194:197], v[202:205], v[114:117]
	v_mfma_f32_16x16x32_bf16 v[106:109], v[186:189], v[210:213], v[106:109]
	v_mfma_f32_16x16x32_bf16 v[98:101], v[194:197], v[210:213], v[98:101]
	v_mfma_f32_16x16x32_bf16 v[90:93], v[186:189], v[218:221], v[90:93]
	v_mfma_f32_16x16x32_bf16 v[82:85], v[194:197], v[218:221], v[82:85]
	v_mfma_f32_16x16x32_bf16 v[74:77], v[186:189], v[226:229], v[74:77]
	v_mfma_f32_16x16x32_bf16 v[66:69], v[194:197], v[226:229], v[66:69]
	v_mfma_f32_16x16x32_bf16 v[122:125], v[190:193], v[206:209], v[122:125]
	v_mfma_f32_16x16x32_bf16 v[114:117], v[198:201], v[206:209], v[114:117]
	v_mfma_f32_16x16x32_bf16 v[106:109], v[190:193], v[214:217], v[106:109]
	v_mfma_f32_16x16x32_bf16 v[98:101], v[198:201], v[214:217], v[98:101]
	v_mfma_f32_16x16x32_bf16 v[90:93], v[190:193], v[222:225], v[90:93]
	v_mfma_f32_16x16x32_bf16 v[82:85], v[198:201], v[222:225], v[82:85]
	v_mfma_f32_16x16x32_bf16 v[74:77], v[190:193], v[230:233], v[74:77]
	v_mfma_f32_16x16x32_bf16 v[66:69], v[198:201], v[230:233], v[66:69]
	s_setprio 0
	s_barrier
	s_add_i32 s66, s57, s46
	v_lshl_add_u64 v[234:235], s[42:43], 0, v[134:135]
	s_mov_b32 m0, s66
	ds_read_b128 v[202:205], v160 offset:16384
	ds_read_b128 v[206:209], v160 offset:17408
	ds_read_b128 v[210:213], v160 offset:18432
	ds_read_b128 v[214:217], v160 offset:19456
	ds_read_b128 v[218:221], v160 offset:20480
	ds_read_b128 v[222:225], v160 offset:21504
	ds_read_b128 v[226:229], v160 offset:22528
	ds_read_b128 v[230:233], v160 offset:23552
	global_load_lds_dwordx4 v[234:235], off
	s_add_i32 m0, s66, 0x2000
	s_add_u32 s66, s42, 0x40000
	v_lshl_add_u64 v[236:237], s[42:43], 0, v[130:131]
	s_addc_u32 s67, s43, 0
	s_add_i32 s68, s58, s46
	global_load_lds_dwordx4 v[236:237], off
	v_lshl_add_u64 v[238:239], s[66:67], 0, v[134:135]
	s_mov_b32 m0, s68
	v_lshl_add_u64 v[240:241], s[44:45], 0, v[132:133]
	global_load_lds_dwordx4 v[238:239], off
	v_lshl_add_u64 v[238:239], s[66:67], 0, v[130:131]
	s_add_i32 m0, s68, 0x2000
	s_nop 0
	global_load_lds_dwordx4 v[238:239], off
	v_lshl_add_u64 v[238:239], s[44:45], 0, v[136:137]
	s_mov_b32 m0, s49
	s_nop 0
	global_load_lds_dwordx4 v[238:239], off
	s_mov_b32 m0, s50
	s_nop 0
	global_load_lds_dwordx4 v[240:241], off
	s_waitcnt vmcnt(8)
	s_waitcnt lgkmcnt(0)
	s_barrier
; #define PG8_STAGE(bufoff, gbase, voff) do { _Pragma("unroll") for (int _i = 0; _i < 2; ++_i) \
;         __builtin_amdgcn_global_load_lds((const unsigned*)((const char*)(gbase) + (voff)[_i]), (LAS unsigned*)(lds + (bufoff) + ldsw + _i * 8192), 16, 0, 0); } while (0)
; #define PG8_LDA(dst, b, h) do { _Pragma("unroll") for (int m = 0; m < 4; ++m) _Pragma("unroll") for (int k = 0; k < 2; ++k) dst[m][k] = *(const LAS bf16x8*)(lds + PG8_SA(b, h) + aoff + m * 2048 + k * 1024); } while (0)
; #define PG8_LDB(dst, b, h) do { _Pragma("unroll") for (int n = 0; n < 2; ++n) _Pragma("unroll") for (int k = 0; k < 2; ++k) dst[n][k] = *(const LAS bf16x8*)(lds + PG8_SB(b, h) + boff + n * 2048 + k * 1024); } while (0)
; #define PG8_MMA(ai, bj, At, Bt) do { __builtin_amdgcn_s_setprio(1); _Pragma("unroll") for (int m = 0; m < 4; ++m) _Pragma("unroll") for (int n = 0; n < 2; ++n) _Pragma("unroll") for (int k = 0; k < 2; ++k) \
;         acc[ai][bj][m][n] = __builtin_amdgcn_mfma_f32_16x16x32_bf16(Bt[n][k], At[m][k], acc[ai][bj][m][n], 0, 0, 0); __builtin_amdgcn_s_setprio(0); } while (0)
; #define PG8_WAIT_V(n) asm volatile("s_waitcnt vmcnt(" #n ")" ::: "memory")
; #define PG8_WAIT_L(n) asm volatile("s_waitcnt lgkmcnt(" #n ")" ::: "memory")
; #define PG8_BAR __builtin_amdgcn_s_barrier()
; #define PG8_SCHED __builtin_amdgcn_sched_barrier(0)
; template <class Epi, class Sched>
; DI void gemm_phase(LAS unsigned char* lds, const Gemm g, const Sched& S, const Epi& E) {
;     ...
;             PG8_WAIT_V(8); PG8_WAIT_L(0); PG8_BAR; PG8_MMA(1, 0, At, B0); PG8_MMA(1, 1, At, B1); PG8_BAR; PG8_SCHED;
;             PG8_LDB(B0, 1, 0); PG8_LDB(B1, 1, 1); PG8_SCHED; PG8_LDA(At, 1, 0); PG8_STAGE(PG8_SA(0, 1), a2 + hstepA, voffA);
;             PG8_WAIT_V(8); PG8_WAIT_L(0); PG8_BAR; PG8_MMA(0, 0, At, B0); PG8_MMA(0, 1, At, B1); PG8_BAR; PG8_SCHED;
	s_setprio 1
	v_mfma_f32_16x16x32_bf16 v[62:65], v[168:171], v[202:205], v[62:65]
	v_mfma_f32_16x16x32_bf16 v[54:57], v[176:179], v[202:205], v[54:57]
	v_mfma_f32_16x16x32_bf16 v[46:49], v[168:171], v[210:213], v[46:49]
	v_mfma_f32_16x16x32_bf16 v[38:41], v[176:179], v[210:213], v[38:41]
	v_mfma_f32_16x16x32_bf16 v[30:33], v[168:171], v[218:221], v[30:33]
	v_mfma_f32_16x16x32_bf16 v[22:25], v[176:179], v[218:221], v[22:25]
	v_mfma_f32_16x16x32_bf16 v[14:17], v[168:171], v[226:229], v[14:17]
	v_mfma_f32_16x16x32_bf16 v[6:9], v[176:179], v[226:229], v[6:9]
	v_mfma_f32_16x16x32_bf16 v[62:65], v[172:175], v[206:209], v[62:65]
	v_mfma_f32_16x16x32_bf16 v[54:57], v[180:183], v[206:209], v[54:57]
	v_mfma_f32_16x16x32_bf16 v[46:49], v[172:175], v[214:217], v[46:49]
	v_mfma_f32_16x16x32_bf16 v[38:41], v[180:183], v[214:217], v[38:41]
	v_mfma_f32_16x16x32_bf16 v[30:33], v[172:175], v[222:225], v[30:33]
	v_mfma_f32_16x16x32_bf16 v[22:25], v[180:183], v[222:225], v[22:25]
	v_mfma_f32_16x16x32_bf16 v[14:17], v[172:175], v[230:233], v[14:17]
	v_mfma_f32_16x16x32_bf16 v[6:9], v[180:183], v[230:233], v[6:9]
	v_mfma_f32_16x16x32_bf16 v[58:61], v[186:189], v[202:205], v[58:61]
	v_mfma_f32_16x16x32_bf16 v[50:53], v[194:197], v[202:205], v[50:53]
	v_mfma_f32_16x16x32_bf16 v[42:45], v[186:189], v[210:213], v[42:45]
	v_mfma_f32_16x16x32_bf16 v[34:37], v[194:197], v[210:213], v[34:37]
	v_mfma_f32_16x16x32_bf16 v[26:29], v[186:189], v[218:221], v[26:29]
	v_mfma_f32_16x16x32_bf16 v[18:21], v[194:197], v[218:221], v[18:21]
	v_mfma_f32_16x16x32_bf16 v[10:13], v[186:189], v[226:229], v[10:13]
	v_mfma_f32_16x16x32_bf16 v[2:5], v[194:197], v[226:229], v[2:5]
	v_mfma_f32_16x16x32_bf16 v[58:61], v[190:193], v[206:209], v[58:61]
	v_mfma_f32_16x16x32_bf16 v[50:53], v[198:201], v[206:209], v[50:53]
	v_mfma_f32_16x16x32_bf16 v[42:45], v[190:193], v[214:217], v[42:45]
	v_mfma_f32_16x16x32_bf16 v[34:37], v[198:201], v[214:217], v[34:37]
	v_mfma_f32_16x16x32_bf16 v[26:29], v[190:193], v[222:225], v[26:29]
	v_mfma_f32_16x16x32_bf16 v[18:21], v[198:201], v[222:225], v[18:21]
	v_mfma_f32_16x16x32_bf16 v[10:13], v[190:193], v[230:233], v[10:13]
	v_mfma_f32_16x16x32_bf16 v[2:5], v[198:201], v[230:233], v[2:5]
	s_setprio 0
	s_barrier
	s_add_i32 s66, 0, 0x18000
	v_add_u32_e32 v167, s66, v158
	s_add_i32 s67, 0, 0x1c000
	ds_read_b128 v[168:171], v167
	ds_read_b128 v[172:175], v167 offset:1024
	ds_read_b128 v[176:179], v167 offset:2048
	ds_read_b128 v[180:183], v167 offset:3072
	v_add_u32_e32 v167, s67, v158
	ds_read_b128 v[186:189], v167
	ds_read_b128 v[190:193], v167 offset:1024
	ds_read_b128 v[194:197], v167 offset:2048
	ds_read_b128 v[198:201], v167 offset:3072
	s_add_u32 s44, s44, 0x40000
	s_addc_u32 s45, s45, 0
	s_mov_b32 m0, s51
	v_lshl_add_u64 v[242:243], s[44:45], 0, v[136:137]
	ds_read_b128 v[202:205], v160 offset:32768
	ds_read_b128 v[206:209], v160 offset:33792
	ds_read_b128 v[210:213], v160 offset:34816
	ds_read_b128 v[214:217], v160 offset:35840
	ds_read_b128 v[218:221], v160 offset:36864
	ds_read_b128 v[222:225], v160 offset:37888
	ds_read_b128 v[226:229], v160 offset:38912
	ds_read_b128 v[230:233], v160 offset:39936
	global_load_lds_dwordx4 v[242:243], off
	v_lshl_add_u64 v[242:243], s[44:45], 0, v[132:133]
	s_mov_b32 m0, s52
	s_nop 0
	global_load_lds_dwordx4 v[242:243], off
	s_waitcnt vmcnt(8)
	s_waitcnt lgkmcnt(0)
	s_barrier
	s_setprio 1
	v_mfma_f32_16x16x32_bf16 v[126:129], v[168:171], v[202:205], v[126:129]
	v_mfma_f32_16x16x32_bf16 v[118:121], v[176:179], v[202:205], v[118:121]
	v_mfma_f32_16x16x32_bf16 v[110:113], v[168:171], v[210:213], v[110:113]
	v_mfma_f32_16x16x32_bf16 v[102:105], v[176:179], v[210:213], v[102:105]
	v_mfma_f32_16x16x32_bf16 v[94:97], v[168:171], v[218:221], v[94:97]
	v_mfma_f32_16x16x32_bf16 v[86:89], v[176:179], v[218:221], v[86:89]
	v_mfma_f32_16x16x32_bf16 v[78:81], v[168:171], v[226:229], v[78:81]
	v_mfma_f32_16x16x32_bf16 v[70:73], v[176:179], v[226:229], v[70:73]
	v_mfma_f32_16x16x32_bf16 v[126:129], v[172:175], v[206:209], v[126:129]
	v_mfma_f32_16x16x32_bf16 v[118:121], v[180:183], v[206:209], v[118:121]
	v_mfma_f32_16x16x32_bf16 v[110:113], v[172:175], v[214:217], v[110:113]
	v_mfma_f32_16x16x32_bf16 v[102:105], v[180:183], v[214:217], v[102:105]
	v_mfma_f32_16x16x32_bf16 v[94:97], v[172:175], v[222:225], v[94:97]
	v_mfma_f32_16x16x32_bf16 v[86:89], v[180:183], v[222:225], v[86:89]
	v_mfma_f32_16x16x32_bf16 v[78:81], v[172:175], v[230:233], v[78:81]
	v_mfma_f32_16x16x32_bf16 v[70:73], v[180:183], v[230:233], v[70:73]
	v_mfma_f32_16x16x32_bf16 v[122:125], v[186:189], v[202:205], v[122:125]
	v_mfma_f32_16x16x32_bf16 v[114:117], v[194:197], v[202:205], v[114:117]
	v_mfma_f32_16x16x32_bf16 v[106:109], v[186:189], v[210:213], v[106:109]
	v_mfma_f32_16x16x32_bf16 v[98:101], v[194:197], v[210:213], v[98:101]
	v_mfma_f32_16x16x32_bf16 v[90:93], v[186:189], v[218:221], v[90:93]
	v_mfma_f32_16x16x32_bf16 v[82:85], v[194:197], v[218:221], v[82:85]
	v_mfma_f32_16x16x32_bf16 v[74:77], v[186:189], v[226:229], v[74:77]
	v_mfma_f32_16x16x32_bf16 v[66:69], v[194:197], v[226:229], v[66:69]
	v_mfma_f32_16x16x32_bf16 v[122:125], v[190:193], v[206:209], v[122:125]
	v_mfma_f32_16x16x32_bf16 v[114:117], v[198:201], v[206:209], v[114:117]
	v_mfma_f32_16x16x32_bf16 v[106:109], v[190:193], v[214:217], v[106:109]
	v_mfma_f32_16x16x32_bf16 v[98:101], v[198:201], v[214:217], v[98:101]
	v_mfma_f32_16x16x32_bf16 v[90:93], v[190:193], v[222:225], v[90:93]
	v_mfma_f32_16x16x32_bf16 v[82:85], v[198:201], v[222:225], v[82:85]
	v_mfma_f32_16x16x32_bf16 v[74:77], v[190:193], v[230:233], v[74:77]
	v_mfma_f32_16x16x32_bf16 v[66:69], v[198:201], v[230:233], v[66:69]
	s_setprio 0
	s_barrier
; DI float fast_exp2(float x) { return __builtin_amdgcn_exp2f(x); }
; DI float fast_rcp(float x) { return __builtin_amdgcn_rcpf(x); }
; #define PG8_STAGE(bufoff, gbase, voff) do { _Pragma("unroll") for (int _i = 0; _i < 2; ++_i) \
;         __builtin_amdgcn_global_load_lds((const unsigned*)((const char*)(gbase) + (voff)[_i]), (LAS unsigned*)(lds + (bufoff) + ldsw + _i * 8192), 16, 0, 0); } while (0)
; #define PG8_LDA(dst, b, h) do { _Pragma("unroll") for (int m = 0; m < 4; ++m) _Pragma("unroll") for (int k = 0; k < 2; ++k) dst[m][k] = *(const LAS bf16x8*)(lds + PG8_SA(b, h) + aoff + m * 2048 + k * 1024); } while (0)
; #define PG8_MMA(ai, bj, At, Bt) do { __builtin_amdgcn_s_setprio(1); _Pragma("unroll") for (int m = 0; m < 4; ++m) _Pragma("unroll") for (int n = 0; n < 2; ++n) _Pragma("unroll") for (int k = 0; k < 2; ++k) \
;         acc[ai][bj][m][n] = __builtin_amdgcn_mfma_f32_16x16x32_bf16(Bt[n][k], At[m][k], acc[ai][bj][m][n], 0, 0, 0); __builtin_amdgcn_s_setprio(0); } while (0)
; #define PG8_WAIT_V(n) asm volatile("s_waitcnt vmcnt(" #n ")" ::: "memory")
; #define PG8_WAIT_L(n) asm volatile("s_waitcnt lgkmcnt(" #n ")" ::: "memory")
; #define PG8_BAR __builtin_amdgcn_s_barrier()
; template <class Epi, class Sched>
; DI void gemm_phase(LAS unsigned char* lds, const Gemm g, const Sched& S, const Epi& E) {
;     ...
;             PG8_LDA(At, 1, 1); PG8_STAGE(PG8_SB(1, 0), b3, voffB); PG8_STAGE(PG8_SB(1, 1), b3 + hstepB, voffB); PG8_STAGE(PG8_SA(1, 0), a3, voffA);
;             PG8_WAIT_V(8); PG8_WAIT_L(0); PG8_BAR; PG8_MMA(1, 0, At, B0); PG8_MMA(1, 1, At, B1); PG8_BAR; PG8_SCHED;
;         }
;         if (wr == 0) PG8_BAR;
;     DI void operator()(Acc& acc, const pg8::Unit& u, int wr, int wc, int fr, int fq, const Pre& pr) const {
;     ...
;                 const int row = u.pm * 256 + ai * 128 + wr * 64 + m * 16 + fr;
;                 const float msq = msq_of(pr.v[ai * 4 + m]), nrl = -1.4426950408889634f * __builtin_amdgcn_rsqf(msq);
;                 f32x4 h[2];
; #pragma unroll
;                 for (int n = 0; n < 2; ++n)
; #pragma unroll
;                     for (int i = 0; i < 4; ++i) { const float ga = acc[ai][0][m][n][i], ua = acc[ai][1][m][n][i];
;                         const float e = fast_exp2(ga * nrl); h[n][i] = (ga * ua) * fast_rcp(__builtin_fmaf(e, msq, msq)); }
;                 store8(H + (size_t)row * FF + col, h[0], h[1]);
	s_add_i32 s44, s66, s46
	v_lshl_add_u64 v[234:235], v[234:235], 0, s[16:17]
	s_mov_b32 m0, s44
	ds_read_b128 v[202:205], v160 offset:49152
	ds_read_b128 v[206:209], v160 offset:50176
	ds_read_b128 v[210:213], v160 offset:51200
	ds_read_b128 v[214:217], v160 offset:52224
	ds_read_b128 v[218:221], v160 offset:53248
	ds_read_b128 v[222:225], v160 offset:54272
	ds_read_b128 v[226:229], v160 offset:55296
	ds_read_b128 v[230:233], v160 offset:56320
	global_load_lds_dwordx4 v[234:235], off
	s_add_i32 m0, s44, 0x2000
	s_add_u32 s42, s42, 0x40080
	v_lshl_add_u64 v[234:235], v[236:237], 0, s[16:17]
	s_addc_u32 s43, s43, 0
	s_add_i32 s44, s67, s46
	global_load_lds_dwordx4 v[234:235], off
	v_lshl_add_u64 v[234:235], s[42:43], 0, v[134:135]
	s_mov_b32 m0, s44
	s_nop 0
	global_load_lds_dwordx4 v[234:235], off
	v_lshl_add_u64 v[234:235], s[42:43], 0, v[130:131]
	s_add_i32 m0, s44, 0x2000
	s_nop 0
	global_load_lds_dwordx4 v[234:235], off
	v_lshl_add_u64 v[234:235], v[238:239], 0, s[16:17]
	s_mov_b32 m0, s54
	s_nop 0
	global_load_lds_dwordx4 v[234:235], off
	v_lshl_add_u64 v[234:235], v[240:241], 0, s[16:17]
	s_mov_b32 m0, s55
	s_nop 0
	global_load_lds_dwordx4 v[234:235], off
	s_waitcnt vmcnt(8)
	s_waitcnt lgkmcnt(0)
	s_barrier
	s_setprio 1
	v_mfma_f32_16x16x32_bf16 v[62:65], v[168:171], v[202:205], v[62:65]
	v_mfma_f32_16x16x32_bf16 v[54:57], v[176:179], v[202:205], v[54:57]
	v_mfma_f32_16x16x32_bf16 v[46:49], v[168:171], v[210:213], v[46:49]
	v_mfma_f32_16x16x32_bf16 v[38:41], v[176:179], v[210:213], v[38:41]
	v_mfma_f32_16x16x32_bf16 v[30:33], v[168:171], v[218:221], v[30:33]
	v_mfma_f32_16x16x32_bf16 v[22:25], v[176:179], v[218:221], v[22:25]
	v_mfma_f32_16x16x32_bf16 v[14:17], v[168:171], v[226:229], v[14:17]
	v_mfma_f32_16x16x32_bf16 v[6:9], v[176:179], v[226:229], v[6:9]
	v_mfma_f32_16x16x32_bf16 v[62:65], v[172:175], v[206:209], v[62:65]
	v_mfma_f32_16x16x32_bf16 v[54:57], v[180:183], v[206:209], v[54:57]
	v_mfma_f32_16x16x32_bf16 v[46:49], v[172:175], v[214:217], v[46:49]
	v_mfma_f32_16x16x32_bf16 v[38:41], v[180:183], v[214:217], v[38:41]
	v_mfma_f32_16x16x32_bf16 v[30:33], v[172:175], v[222:225], v[30:33]
	v_mfma_f32_16x16x32_bf16 v[22:25], v[180:183], v[222:225], v[22:25]
	v_mfma_f32_16x16x32_bf16 v[14:17], v[172:175], v[230:233], v[14:17]
	v_mfma_f32_16x16x32_bf16 v[6:9], v[180:183], v[230:233], v[6:9]
	v_mfma_f32_16x16x32_bf16 v[58:61], v[186:189], v[202:205], v[58:61]
	v_mfma_f32_16x16x32_bf16 v[50:53], v[194:197], v[202:205], v[50:53]
	v_mfma_f32_16x16x32_bf16 v[42:45], v[186:189], v[210:213], v[42:45]
	v_mfma_f32_16x16x32_bf16 v[34:37], v[194:197], v[210:213], v[34:37]
	v_mfma_f32_16x16x32_bf16 v[26:29], v[186:189], v[218:221], v[26:29]
	v_mfma_f32_16x16x32_bf16 v[18:21], v[194:197], v[218:221], v[18:21]
	v_mfma_f32_16x16x32_bf16 v[10:13], v[186:189], v[226:229], v[10:13]
	v_mfma_f32_16x16x32_bf16 v[2:5], v[194:197], v[226:229], v[2:5]
	v_mfma_f32_16x16x32_bf16 v[58:61], v[190:193], v[206:209], v[58:61]
	v_mfma_f32_16x16x32_bf16 v[50:53], v[198:201], v[206:209], v[50:53]
	v_mfma_f32_16x16x32_bf16 v[42:45], v[190:193], v[214:217], v[42:45]
	v_mfma_f32_16x16x32_bf16 v[34:37], v[198:201], v[214:217], v[34:37]
	v_mfma_f32_16x16x32_bf16 v[26:29], v[190:193], v[222:225], v[26:29]
	v_mfma_f32_16x16x32_bf16 v[18:21], v[198:201], v[222:225], v[18:21]
	v_mfma_f32_16x16x32_bf16 v[10:13], v[190:193], v[230:233], v[10:13]
	v_mfma_f32_16x16x32_bf16 v[2:5], v[198:201], v[230:233], v[2:5]
	s_setprio 0
	s_barrier
	s_add_i32 s65, s65, 2
	s_add_u32 s40, s40, 0x100
	s_addc_u32 s41, s41, 0
	s_add_u32 s63, s63, 0x100
	s_addc_u32 s64, s64, 0
	s_cmp_gt_u32 s65, 13
	s_cbranch_scc0 .LBB0_179
	s_mov_b32 s99, 1
	s_and_b64 vcc, exec, s[18:19]
	s_cbranch_vccz .LBB0_182
	s_barrier
.LBB0_182:
	v_fmamk_f32 v186, v166, 0x3a800000, v161
	v_rsq_f32_e32 v189, v186
	v_lshl_or_b32 v202, s60, 7, v159
	v_lshlrev_b32_e32 v202, 1, v202
	v_mad_u32_u24 v194, v156, s59, v202
	v_mul_f32_e32 v188, 0xbfb8aa3b, v189
	v_fmamk_f32 v190, v165, 0x3a800000, v161
	v_rsq_f32_e32 v193, v190
	v_add_u32_e32 v195, 0x16000, v194
	v_add_u32_e32 v196, 0x2c000, v194
	v_add_u32_e32 v197, 0x42000, v194
	v_add_u32_e32 v198, 0xb0000, v194
	v_add_u32_e32 v199, 0xc6000, v194
	v_add_u32_e32 v200, 0xdc000, v194
	v_add_u32_e32 v201, 0xf2000, v194
	v_mul_f32_e32 v192, 0xbfb8aa3b, v193
	v_pk_mul_f32 v[122:123], v[126:127], v[122:123]
	v_pk_mul_f32 v[124:125], v[128:129], v[124:125]
	v_pk_mul_f32 v[114:115], v[118:119], v[114:115]
	v_pk_mul_f32 v[116:117], v[120:121], v[116:117]
	v_pk_mul_f32 v[126:127], v[126:127], v[188:189] op_sel_hi:[1,0]
	v_pk_mul_f32 v[128:129], v[128:129], v[188:189] op_sel_hi:[1,0]
	v_pk_mul_f32 v[118:119], v[118:119], v[188:189] op_sel_hi:[1,0]
	v_pk_mul_f32 v[120:121], v[120:121], v[188:189] op_sel_hi:[1,0]
	v_exp_f32_e32 v126, v126
	v_exp_f32_e32 v127, v127
	v_exp_f32_e32 v128, v128
	v_exp_f32_e32 v129, v129
	v_exp_f32_e32 v118, v118
	v_exp_f32_e32 v119, v119
	v_exp_f32_e32 v120, v120
	v_exp_f32_e32 v121, v121
	v_pk_fma_f32 v[126:127], v[126:127], v[186:187], v[186:187] op_sel_hi:[1,0,0]
	v_pk_fma_f32 v[128:129], v[128:129], v[186:187], v[186:187] op_sel_hi:[1,0,0]
	v_pk_fma_f32 v[118:119], v[118:119], v[186:187], v[186:187] op_sel_hi:[1,0,0]
	v_pk_fma_f32 v[120:121], v[120:121], v[186:187], v[186:187] op_sel_hi:[1,0,0]
	v_rcp_f32_e32 v126, v126
	v_rcp_f32_e32 v127, v127
	v_rcp_f32_e32 v128, v128
	v_rcp_f32_e32 v129, v129
	v_rcp_f32_e32 v118, v118
	v_rcp_f32_e32 v119, v119
	v_rcp_f32_e32 v120, v120
	v_rcp_f32_e32 v121, v121
	v_fmamk_f32 v186, v164, 0x3a800000, v161
	v_rsq_f32_e32 v189, v186
	v_pk_mul_f32 v[122:123], v[126:127], v[122:123]
	v_pk_mul_f32 v[124:125], v[128:129], v[124:125]
; DI float fast_exp2(float x) { return __builtin_amdgcn_exp2f(x); }
; DI float fast_rcp(float x) { return __builtin_amdgcn_rcpf(x); }
;     DI void operator()(Acc& acc, const pg8::Unit& u, int wr, int wc, int fr, int fq, const Pre& pr) const {
;     ...
;                 const int row = u.pm * 256 + ai * 128 + wr * 64 + m * 16 + fr;
;                 const float msq = msq_of(pr.v[ai * 4 + m]), nrl = -1.4426950408889634f * __builtin_amdgcn_rsqf(msq);
;                 f32x4 h[2];
; #pragma unroll
;                 for (int n = 0; n < 2; ++n)
; #pragma unroll
;                     for (int i = 0; i < 4; ++i) { const float ga = acc[ai][0][m][n][i], ua = acc[ai][1][m][n][i];
;                         const float e = fast_exp2(ga * nrl); h[n][i] = (ga * ua) * fast_rcp(__builtin_fmaf(e, msq, msq)); }
;                 store8(H + (size_t)row * FF + col, h[0], h[1]);
	v_pk_mul_f32 v[114:115], v[118:119], v[114:115]
	v_pk_mul_f32 v[116:117], v[120:121], v[116:117]
	v_cvt_pk_bf16_f32 v126, v122, v123
	v_cvt_pk_bf16_f32 v127, v124, v125
	v_cvt_pk_bf16_f32 v128, v114, v115
	v_cvt_pk_bf16_f32 v129, v116, v117
	v_mul_f32_e32 v188, 0xbfb8aa3b, v189
	v_pk_mul_f32 v[106:107], v[110:111], v[106:107]
	v_pk_mul_f32 v[108:109], v[112:113], v[108:109]
	v_pk_mul_f32 v[98:99], v[102:103], v[98:99]
	v_pk_mul_f32 v[100:101], v[104:105], v[100:101]
	v_pk_mul_f32 v[110:111], v[110:111], v[192:193] op_sel_hi:[1,0]
	v_pk_mul_f32 v[112:113], v[112:113], v[192:193] op_sel_hi:[1,0]
	v_pk_mul_f32 v[102:103], v[102:103], v[192:193] op_sel_hi:[1,0]
	v_pk_mul_f32 v[104:105], v[104:105], v[192:193] op_sel_hi:[1,0]
	v_exp_f32_e32 v110, v110
	v_exp_f32_e32 v111, v111
	v_exp_f32_e32 v112, v112
	v_exp_f32_e32 v113, v113
	v_exp_f32_e32 v102, v102
	v_exp_f32_e32 v103, v103
	v_exp_f32_e32 v104, v104
	v_exp_f32_e32 v105, v105
	global_store_dwordx4 v194, v[126:129], s[10:11]
	v_pk_fma_f32 v[110:111], v[110:111], v[190:191], v[190:191] op_sel_hi:[1,0,0]
	v_pk_fma_f32 v[112:113], v[112:113], v[190:191], v[190:191] op_sel_hi:[1,0,0]
	v_pk_fma_f32 v[102:103], v[102:103], v[190:191], v[190:191] op_sel_hi:[1,0,0]
	v_pk_fma_f32 v[104:105], v[104:105], v[190:191], v[190:191] op_sel_hi:[1,0,0]
	v_rcp_f32_e32 v110, v110
	v_rcp_f32_e32 v111, v111
	v_rcp_f32_e32 v112, v112
	v_rcp_f32_e32 v113, v113
	v_rcp_f32_e32 v102, v102
	v_rcp_f32_e32 v103, v103
	v_rcp_f32_e32 v104, v104
	v_rcp_f32_e32 v105, v105
	v_fmamk_f32 v190, v157, 0x3a800000, v161
	v_rsq_f32_e32 v193, v190
	v_pk_mul_f32 v[106:107], v[110:111], v[106:107]
	v_pk_mul_f32 v[108:109], v[112:113], v[108:109]
	v_pk_mul_f32 v[98:99], v[102:103], v[98:99]
	v_pk_mul_f32 v[100:101], v[104:105], v[100:101]
	v_cvt_pk_bf16_f32 v110, v106, v107
	v_cvt_pk_bf16_f32 v111, v108, v109
	v_cvt_pk_bf16_f32 v112, v98, v99
	v_cvt_pk_bf16_f32 v113, v100, v101
	v_mul_f32_e32 v192, 0xbfb8aa3b, v193
	v_pk_mul_f32 v[90:91], v[94:95], v[90:91]
	v_pk_mul_f32 v[92:93], v[96:97], v[92:93]
	v_pk_mul_f32 v[82:83], v[86:87], v[82:83]
	v_pk_mul_f32 v[84:85], v[88:89], v[84:85]
	v_pk_mul_f32 v[94:95], v[94:95], v[188:189] op_sel_hi:[1,0]
	v_pk_mul_f32 v[96:97], v[96:97], v[188:189] op_sel_hi:[1,0]
	v_pk_mul_f32 v[86:87], v[86:87], v[188:189] op_sel_hi:[1,0]
	v_pk_mul_f32 v[88:89], v[88:89], v[188:189] op_sel_hi:[1,0]
	v_exp_f32_e32 v94, v94
	v_exp_f32_e32 v95, v95
	v_exp_f32_e32 v96, v96
	v_exp_f32_e32 v97, v97
	v_exp_f32_e32 v86, v86
	v_exp_f32_e32 v87, v87
	v_exp_f32_e32 v88, v88
	v_exp_f32_e32 v89, v89
	global_store_dwordx4 v195, v[110:113], s[10:11]
	v_pk_fma_f32 v[94:95], v[94:95], v[186:187], v[186:187] op_sel_hi:[1,0,0]
	v_pk_fma_f32 v[96:97], v[96:97], v[186:187], v[186:187] op_sel_hi:[1,0,0]
	v_pk_fma_f32 v[86:87], v[86:87], v[186:187], v[186:187] op_sel_hi:[1,0,0]
	v_pk_fma_f32 v[88:89], v[88:89], v[186:187], v[186:187] op_sel_hi:[1,0,0]
	v_rcp_f32_e32 v94, v94
	v_rcp_f32_e32 v95, v95
	v_rcp_f32_e32 v96, v96
	v_rcp_f32_e32 v97, v97
	v_rcp_f32_e32 v86, v86
	v_rcp_f32_e32 v87, v87
	v_rcp_f32_e32 v88, v88
	v_rcp_f32_e32 v89, v89
	v_fmamk_f32 v186, v155, 0x3a800000, v161
	v_rsq_f32_e32 v189, v186
	v_pk_mul_f32 v[90:91], v[94:95], v[90:91]
	v_pk_mul_f32 v[92:93], v[96:97], v[92:93]
	v_pk_mul_f32 v[82:83], v[86:87], v[82:83]
	v_pk_mul_f32 v[84:85], v[88:89], v[84:85]
	v_cvt_pk_bf16_f32 v94, v90, v91
	v_cvt_pk_bf16_f32 v95, v92, v93
	v_cvt_pk_bf16_f32 v96, v82, v83
	v_cvt_pk_bf16_f32 v97, v84, v85
	v_mul_f32_e32 v188, 0xbfb8aa3b, v189
	v_pk_mul_f32 v[74:75], v[78:79], v[74:75]
	v_pk_mul_f32 v[76:77], v[80:81], v[76:77]
	v_pk_mul_f32 v[66:67], v[70:71], v[66:67]
	v_pk_mul_f32 v[68:69], v[72:73], v[68:69]
	v_pk_mul_f32 v[78:79], v[78:79], v[192:193] op_sel_hi:[1,0]
	v_pk_mul_f32 v[80:81], v[80:81], v[192:193] op_sel_hi:[1,0]
	v_pk_mul_f32 v[70:71], v[70:71], v[192:193] op_sel_hi:[1,0]
	v_pk_mul_f32 v[72:73], v[72:73], v[192:193] op_sel_hi:[1,0]
	v_exp_f32_e32 v78, v78
	v_exp_f32_e32 v79, v79
	v_exp_f32_e32 v80, v80
	v_exp_f32_e32 v81, v81
	v_exp_f32_e32 v70, v70
	v_exp_f32_e32 v71, v71
	v_exp_f32_e32 v72, v72
	v_exp_f32_e32 v73, v73
	global_store_dwordx4 v196, v[94:97], s[10:11]
	v_pk_fma_f32 v[78:79], v[78:79], v[190:191], v[190:191] op_sel_hi:[1,0,0]
	v_pk_fma_f32 v[80:81], v[80:81], v[190:191], v[190:191] op_sel_hi:[1,0,0]
	v_pk_fma_f32 v[70:71], v[70:71], v[190:191], v[190:191] op_sel_hi:[1,0,0]
	v_pk_fma_f32 v[72:73], v[72:73], v[190:191], v[190:191] op_sel_hi:[1,0,0]
	v_rcp_f32_e32 v78, v78
	v_rcp_f32_e32 v79, v79
	v_rcp_f32_e32 v80, v80
	v_rcp_f32_e32 v81, v81
	v_rcp_f32_e32 v70, v70
	v_rcp_f32_e32 v71, v71
	v_rcp_f32_e32 v72, v72
	v_rcp_f32_e32 v73, v73
	v_fmamk_f32 v190, v153, 0x3a800000, v161
	v_rsq_f32_e32 v193, v190
	v_pk_mul_f32 v[74:75], v[78:79], v[74:75]
	v_pk_mul_f32 v[76:77], v[80:81], v[76:77]
	v_pk_mul_f32 v[66:67], v[70:71], v[66:67]
	v_pk_mul_f32 v[68:69], v[72:73], v[68:69]
	v_cvt_pk_bf16_f32 v78, v74, v75
	v_cvt_pk_bf16_f32 v79, v76, v77
	v_cvt_pk_bf16_f32 v80, v66, v67
	v_cvt_pk_bf16_f32 v81, v68, v69
	v_mul_f32_e32 v192, 0xbfb8aa3b, v193
	v_pk_mul_f32 v[58:59], v[62:63], v[58:59]
	v_pk_mul_f32 v[60:61], v[64:65], v[60:61]
	v_pk_mul_f32 v[50:51], v[54:55], v[50:51]
	v_pk_mul_f32 v[52:53], v[56:57], v[52:53]
	v_pk_mul_f32 v[62:63], v[62:63], v[188:189] op_sel_hi:[1,0]
	v_pk_mul_f32 v[64:65], v[64:65], v[188:189] op_sel_hi:[1,0]
	v_pk_mul_f32 v[54:55], v[54:55], v[188:189] op_sel_hi:[1,0]
	v_pk_mul_f32 v[56:57], v[56:57], v[188:189] op_sel_hi:[1,0]
	v_exp_f32_e32 v62, v62
	v_exp_f32_e32 v63, v63
	v_exp_f32_e32 v64, v64
	v_exp_f32_e32 v65, v65
	v_exp_f32_e32 v54, v54
	v_exp_f32_e32 v55, v55
; DI float fast_exp2(float x) { return __builtin_amdgcn_exp2f(x); }
; DI float fast_rcp(float x) { return __builtin_amdgcn_rcpf(x); }
;     DI void operator()(Acc& acc, const pg8::Unit& u, int wr, int wc, int fr, int fq, const Pre& pr) const {
;     ...
;                 const int row = u.pm * 256 + ai * 128 + wr * 64 + m * 16 + fr;
;                 const float msq = msq_of(pr.v[ai * 4 + m]), nrl = -1.4426950408889634f * __builtin_amdgcn_rsqf(msq);
;                 f32x4 h[2];
; #pragma unroll
;                 for (int n = 0; n < 2; ++n)
; #pragma unroll
;                     for (int i = 0; i < 4; ++i) { const float ga = acc[ai][0][m][n][i], ua = acc[ai][1][m][n][i];
;                         const float e = fast_exp2(ga * nrl); h[n][i] = (ga * ua) * fast_rcp(__builtin_fmaf(e, msq, msq)); }
;                 store8(H + (size_t)row * FF + col, h[0], h[1]);
	v_exp_f32_e32 v56, v56
	v_exp_f32_e32 v57, v57
	global_store_dwordx4 v197, v[78:81], s[10:11]
	v_pk_fma_f32 v[62:63], v[62:63], v[186:187], v[186:187] op_sel_hi:[1,0,0]
	v_pk_fma_f32 v[64:65], v[64:65], v[186:187], v[186:187] op_sel_hi:[1,0,0]
	v_pk_fma_f32 v[54:55], v[54:55], v[186:187], v[186:187] op_sel_hi:[1,0,0]
	v_pk_fma_f32 v[56:57], v[56:57], v[186:187], v[186:187] op_sel_hi:[1,0,0]
	v_rcp_f32_e32 v62, v62
	v_rcp_f32_e32 v63, v63
	v_rcp_f32_e32 v64, v64
	v_rcp_f32_e32 v65, v65
	v_rcp_f32_e32 v54, v54
	v_rcp_f32_e32 v55, v55
	v_rcp_f32_e32 v56, v56
	v_rcp_f32_e32 v57, v57
	v_fmamk_f32 v186, v151, 0x3a800000, v161
	v_rsq_f32_e32 v189, v186
	v_pk_mul_f32 v[58:59], v[62:63], v[58:59]
	v_pk_mul_f32 v[60:61], v[64:65], v[60:61]
	v_pk_mul_f32 v[50:51], v[54:55], v[50:51]
	v_pk_mul_f32 v[52:53], v[56:57], v[52:53]
	v_cvt_pk_bf16_f32 v62, v58, v59
	v_cvt_pk_bf16_f32 v63, v60, v61
	v_cvt_pk_bf16_f32 v64, v50, v51
	v_cvt_pk_bf16_f32 v65, v52, v53
	v_mul_f32_e32 v188, 0xbfb8aa3b, v189
	v_pk_mul_f32 v[42:43], v[46:47], v[42:43]
	v_pk_mul_f32 v[44:45], v[48:49], v[44:45]
	v_pk_mul_f32 v[34:35], v[38:39], v[34:35]
	v_pk_mul_f32 v[36:37], v[40:41], v[36:37]
	v_pk_mul_f32 v[46:47], v[46:47], v[192:193] op_sel_hi:[1,0]
	v_pk_mul_f32 v[48:49], v[48:49], v[192:193] op_sel_hi:[1,0]
	v_pk_mul_f32 v[38:39], v[38:39], v[192:193] op_sel_hi:[1,0]
	v_pk_mul_f32 v[40:41], v[40:41], v[192:193] op_sel_hi:[1,0]
	v_exp_f32_e32 v46, v46
	v_exp_f32_e32 v47, v47
	v_exp_f32_e32 v48, v48
	v_exp_f32_e32 v49, v49
	v_exp_f32_e32 v38, v38
	v_exp_f32_e32 v39, v39
	v_exp_f32_e32 v40, v40
	v_exp_f32_e32 v41, v41
	global_store_dwordx4 v198, v[62:65], s[10:11]
	v_pk_fma_f32 v[46:47], v[46:47], v[190:191], v[190:191] op_sel_hi:[1,0,0]
	v_pk_fma_f32 v[48:49], v[48:49], v[190:191], v[190:191] op_sel_hi:[1,0,0]
	v_pk_fma_f32 v[38:39], v[38:39], v[190:191], v[190:191] op_sel_hi:[1,0,0]
	v_pk_fma_f32 v[40:41], v[40:41], v[190:191], v[190:191] op_sel_hi:[1,0,0]
	v_rcp_f32_e32 v46, v46
	v_rcp_f32_e32 v47, v47
	v_rcp_f32_e32 v48, v48
	v_rcp_f32_e32 v49, v49
	v_rcp_f32_e32 v38, v38
	v_rcp_f32_e32 v39, v39
	v_rcp_f32_e32 v40, v40
	v_rcp_f32_e32 v41, v41
	v_fmamk_f32 v190, v149, 0x3a800000, v161
	v_rsq_f32_e32 v193, v190
	v_pk_mul_f32 v[42:43], v[46:47], v[42:43]
	v_pk_mul_f32 v[44:45], v[48:49], v[44:45]
	v_pk_mul_f32 v[34:35], v[38:39], v[34:35]
	v_pk_mul_f32 v[36:37], v[40:41], v[36:37]
	v_cvt_pk_bf16_f32 v46, v42, v43
	v_cvt_pk_bf16_f32 v47, v44, v45
	v_cvt_pk_bf16_f32 v48, v34, v35
	v_cvt_pk_bf16_f32 v49, v36, v37
	v_mul_f32_e32 v192, 0xbfb8aa3b, v193
	v_pk_mul_f32 v[26:27], v[30:31], v[26:27]
	v_pk_mul_f32 v[28:29], v[32:33], v[28:29]
	v_pk_mul_f32 v[18:19], v[22:23], v[18:19]
	v_pk_mul_f32 v[20:21], v[24:25], v[20:21]
	v_pk_mul_f32 v[30:31], v[30:31], v[188:189] op_sel_hi:[1,0]
	v_pk_mul_f32 v[32:33], v[32:33], v[188:189] op_sel_hi:[1,0]
	v_pk_mul_f32 v[22:23], v[22:23], v[188:189] op_sel_hi:[1,0]
	v_pk_mul_f32 v[24:25], v[24:25], v[188:189] op_sel_hi:[1,0]
	v_exp_f32_e32 v30, v30
	v_exp_f32_e32 v31, v31
	v_exp_f32_e32 v32, v32
	v_exp_f32_e32 v33, v33
	v_exp_f32_e32 v22, v22
	v_exp_f32_e32 v23, v23
	v_exp_f32_e32 v24, v24
	v_exp_f32_e32 v25, v25
	global_store_dwordx4 v199, v[46:49], s[10:11]
	v_pk_fma_f32 v[30:31], v[30:31], v[186:187], v[186:187] op_sel_hi:[1,0,0]
	v_pk_fma_f32 v[32:33], v[32:33], v[186:187], v[186:187] op_sel_hi:[1,0,0]
	v_pk_fma_f32 v[22:23], v[22:23], v[186:187], v[186:187] op_sel_hi:[1,0,0]
	v_pk_fma_f32 v[24:25], v[24:25], v[186:187], v[186:187] op_sel_hi:[1,0,0]
	v_rcp_f32_e32 v30, v30
	v_rcp_f32_e32 v31, v31
	v_rcp_f32_e32 v32, v32
	v_rcp_f32_e32 v33, v33
	v_rcp_f32_e32 v22, v22
	v_rcp_f32_e32 v23, v23
	v_rcp_f32_e32 v24, v24
	v_rcp_f32_e32 v25, v25
	v_pk_mul_f32 v[26:27], v[30:31], v[26:27]
	v_pk_mul_f32 v[28:29], v[32:33], v[28:29]
	v_pk_mul_f32 v[18:19], v[22:23], v[18:19]
	v_pk_mul_f32 v[20:21], v[24:25], v[20:21]
	v_cvt_pk_bf16_f32 v30, v26, v27
	v_cvt_pk_bf16_f32 v31, v28, v29
	v_cvt_pk_bf16_f32 v32, v18, v19
	v_cvt_pk_bf16_f32 v33, v20, v21
	v_pk_mul_f32 v[10:11], v[14:15], v[10:11]
	v_pk_mul_f32 v[12:13], v[16:17], v[12:13]
	v_pk_mul_f32 v[2:3], v[6:7], v[2:3]
	v_pk_mul_f32 v[4:5], v[8:9], v[4:5]
	v_pk_mul_f32 v[14:15], v[14:15], v[192:193] op_sel_hi:[1,0]
	v_pk_mul_f32 v[16:17], v[16:17], v[192:193] op_sel_hi:[1,0]
	v_pk_mul_f32 v[6:7], v[6:7], v[192:193] op_sel_hi:[1,0]
	v_pk_mul_f32 v[8:9], v[8:9], v[192:193] op_sel_hi:[1,0]
	v_exp_f32_e32 v14, v14
	v_exp_f32_e32 v15, v15
	v_exp_f32_e32 v16, v16
	v_exp_f32_e32 v17, v17
	v_exp_f32_e32 v6, v6
	v_exp_f32_e32 v7, v7
	v_exp_f32_e32 v8, v8
	v_exp_f32_e32 v9, v9
	global_store_dwordx4 v200, v[30:33], s[10:11]
	v_pk_fma_f32 v[14:15], v[14:15], v[190:191], v[190:191] op_sel_hi:[1,0,0]
	v_pk_fma_f32 v[16:17], v[16:17], v[190:191], v[190:191] op_sel_hi:[1,0,0]
	v_pk_fma_f32 v[6:7], v[6:7], v[190:191], v[190:191] op_sel_hi:[1,0,0]
	v_pk_fma_f32 v[8:9], v[8:9], v[190:191], v[190:191] op_sel_hi:[1,0,0]
	v_rcp_f32_e32 v14, v14
	v_rcp_f32_e32 v15, v15
	v_rcp_f32_e32 v16, v16
	v_rcp_f32_e32 v17, v17
	v_rcp_f32_e32 v6, v6
	v_rcp_f32_e32 v7, v7
	v_rcp_f32_e32 v8, v8
	v_rcp_f32_e32 v9, v9
	v_pk_mul_f32 v[10:11], v[14:15], v[10:11]
	v_pk_mul_f32 v[12:13], v[16:17], v[12:13]
	v_pk_mul_f32 v[2:3], v[6:7], v[2:3]
	v_pk_mul_f32 v[4:5], v[8:9], v[4:5]
	v_cvt_pk_bf16_f32 v14, v10, v11
	v_cvt_pk_bf16_f32 v15, v12, v13
	v_cvt_pk_bf16_f32 v16, v2, v3
	v_cvt_pk_bf16_f32 v17, v4, v5
	s_waitcnt vmcnt(7)
	s_andn2_b64 vcc, exec, s[4:5]
	s_mov_b64 s[4:5], -1
	global_store_dwordx4 v201, v[14:17], s[10:11]
	s_cbranch_vccnz .LBB0_175
	s_andn2_b64 vcc, exec, s[8:9]
	s_cbranch_vccnz .LBB0_174
	s_barrier
	s_branch .LBB0_174

; #define PG8_STAGE(bufoff, gbase, voff) do { _Pragma("unroll") for (int _i = 0; _i < 2; ++_i) \
;         __builtin_amdgcn_global_load_lds((const unsigned*)((const char*)(gbase) + (voff)[_i]), (LAS unsigned*)(lds + (bufoff) + ldsw + _i * 8192), 16, 0, 0); } while (0)
; #define PG8_LDA(dst, b, h) do { _Pragma("unroll") for (int m = 0; m < 4; ++m) _Pragma("unroll") for (int k = 0; k < 2; ++k) dst[m][k] = *(const LAS bf16x8*)(lds + PG8_SA(b, h) + aoff + m * 2048 + k * 1024); } while (0)
; #define PG8_LDB(dst, b, h) do { _Pragma("unroll") for (int n = 0; n < 2; ++n) _Pragma("unroll") for (int k = 0; k < 2; ++k) dst[n][k] = *(const LAS bf16x8*)(lds + PG8_SB(b, h) + boff + n * 2048 + k * 1024); } while (0)
; #define PG8_MMA(ai, bj, At, Bt) do { __builtin_amdgcn_s_setprio(1); _Pragma("unroll") for (int m = 0; m < 4; ++m) _Pragma("unroll") for (int n = 0; n < 2; ++n) _Pragma("unroll") for (int k = 0; k < 2; ++k) \
;         acc[ai][bj][m][n] = __builtin_amdgcn_mfma_f32_16x16x32_bf16(Bt[n][k], At[m][k], acc[ai][bj][m][n], 0, 0, 0); __builtin_amdgcn_s_setprio(0); } while (0)
; #define PG8_WAIT_V(n) asm volatile("s_waitcnt vmcnt(" #n ")" ::: "memory")
; #define PG8_WAIT_L(n) asm volatile("s_waitcnt lgkmcnt(" #n ")" ::: "memory")
; #define PG8_BAR __builtin_amdgcn_s_barrier()
; #define PG8_SCHED __builtin_amdgcn_sched_barrier(0)
; template <class Epi, class Sched>
; DI void gemm_phase(LAS unsigned char* lds, const Gemm g, const Sched& S, const Epi& E) {
;     ...
;             PG8_LDB(B0, 0, 0); PG8_LDB(B1, 0, 1); PG8_SCHED; PG8_LDA(At, 0, 0); PG8_STAGE(PG8_SA(1, 1), a1 + hstepA, voffA);
;             PG8_WAIT_V(8); PG8_WAIT_L(0); PG8_BAR; PG8_MMA(0, 0, At, B0); PG8_MMA(0, 1, At, B1); PG8_BAR; PG8_SCHED;
;             PG8_LDA(At, 0, 1); PG8_STAGE(PG8_SB(0, 0), b2, voffB); PG8_STAGE(PG8_SB(0, 1), b2 + hstepB, voffB); PG8_STAGE(PG8_SA(0, 0), a2, voffA);
;             PG8_WAIT_V(8); PG8_WAIT_L(0); PG8_BAR; PG8_MMA(1, 0, At, B0); PG8_MMA(1, 1, At, B1); PG8_BAR; PG8_SCHED;
.LBB0_1234:
	ds_read_b128 v[166:169], v160
	ds_read_b128 v[170:173], v160 offset:1024
	ds_read_b128 v[174:177], v160 offset:2048
	ds_read_b128 v[178:181], v160 offset:3072
	ds_read_b128 v[186:189], v161
	ds_read_b128 v[190:193], v161 offset:1024
	ds_read_b128 v[194:197], v161 offset:2048
	ds_read_b128 v[198:201], v161 offset:3072
	s_add_u32 s42, s40, 0xfffc0080
	s_addc_u32 s43, s41, -1
	s_cmp_eq_u32 s65, 12
	s_cselect_b32 s45, s35, s43
	s_cselect_b32 s44, s61, s42
	s_cselect_b32 s43, s21, s64
	s_cselect_b32 s42, s62, s63
	v_lshl_add_u64 v[182:183], s[40:41], 0, v[138:139]
	s_add_i32 m0, s49, 0xc000
	ds_read_b128 v[202:205], v158
	ds_read_b128 v[206:209], v158 offset:1024
	ds_read_b128 v[210:213], v158 offset:2048
	ds_read_b128 v[214:217], v158 offset:3072
	ds_read_b128 v[218:221], v158 offset:4096
	ds_read_b128 v[222:225], v158 offset:5120
	ds_read_b128 v[226:229], v158 offset:6144
	ds_read_b128 v[230:233], v158 offset:7168
	global_load_lds_dwordx4 v[182:183], off
	v_lshl_add_u64 v[182:183], s[40:41], 0, v[140:141]
	s_add_i32 m0, s49, 0xe000
	s_nop 0
	global_load_lds_dwordx4 v[182:183], off
	s_waitcnt vmcnt(8)
	s_waitcnt lgkmcnt(0)
	s_barrier
	s_setprio 1
	v_mfma_f32_16x16x32_bf16 v[126:129], v[166:169], v[202:205], v[126:129]
	v_mfma_f32_16x16x32_bf16 v[118:121], v[174:177], v[202:205], v[118:121]
	v_mfma_f32_16x16x32_bf16 v[110:113], v[166:169], v[210:213], v[110:113]
	v_mfma_f32_16x16x32_bf16 v[102:105], v[174:177], v[210:213], v[102:105]
	v_mfma_f32_16x16x32_bf16 v[94:97], v[166:169], v[218:221], v[94:97]
	v_mfma_f32_16x16x32_bf16 v[86:89], v[174:177], v[218:221], v[86:89]
	v_mfma_f32_16x16x32_bf16 v[78:81], v[166:169], v[226:229], v[78:81]
	v_mfma_f32_16x16x32_bf16 v[70:73], v[174:177], v[226:229], v[70:73]
	v_mfma_f32_16x16x32_bf16 v[126:129], v[170:173], v[206:209], v[126:129]
	v_mfma_f32_16x16x32_bf16 v[118:121], v[178:181], v[206:209], v[118:121]
	v_mfma_f32_16x16x32_bf16 v[110:113], v[170:173], v[214:217], v[110:113]
	v_mfma_f32_16x16x32_bf16 v[102:105], v[178:181], v[214:217], v[102:105]
	v_mfma_f32_16x16x32_bf16 v[94:97], v[170:173], v[222:225], v[94:97]
	v_mfma_f32_16x16x32_bf16 v[86:89], v[178:181], v[222:225], v[86:89]
	v_mfma_f32_16x16x32_bf16 v[78:81], v[170:173], v[230:233], v[78:81]
	v_mfma_f32_16x16x32_bf16 v[70:73], v[178:181], v[230:233], v[70:73]
	v_mfma_f32_16x16x32_bf16 v[122:125], v[186:189], v[202:205], v[122:125]
	v_mfma_f32_16x16x32_bf16 v[114:117], v[194:197], v[202:205], v[114:117]
	v_mfma_f32_16x16x32_bf16 v[106:109], v[186:189], v[210:213], v[106:109]
	v_mfma_f32_16x16x32_bf16 v[98:101], v[194:197], v[210:213], v[98:101]
	v_mfma_f32_16x16x32_bf16 v[90:93], v[186:189], v[218:221], v[90:93]
	v_mfma_f32_16x16x32_bf16 v[82:85], v[194:197], v[218:221], v[82:85]
	v_mfma_f32_16x16x32_bf16 v[74:77], v[186:189], v[226:229], v[74:77]
	v_mfma_f32_16x16x32_bf16 v[66:69], v[194:197], v[226:229], v[66:69]
	v_mfma_f32_16x16x32_bf16 v[122:125], v[190:193], v[206:209], v[122:125]
	v_mfma_f32_16x16x32_bf16 v[114:117], v[198:201], v[206:209], v[114:117]
	v_mfma_f32_16x16x32_bf16 v[106:109], v[190:193], v[214:217], v[106:109]
	v_mfma_f32_16x16x32_bf16 v[98:101], v[198:201], v[214:217], v[98:101]
	v_mfma_f32_16x16x32_bf16 v[90:93], v[190:193], v[222:225], v[90:93]
	v_mfma_f32_16x16x32_bf16 v[82:85], v[198:201], v[222:225], v[82:85]
	v_mfma_f32_16x16x32_bf16 v[74:77], v[190:193], v[230:233], v[74:77]
	v_mfma_f32_16x16x32_bf16 v[66:69], v[198:201], v[230:233], v[66:69]
	s_setprio 0
	s_barrier
	s_add_i32 s66, s57, s46
	v_lshl_add_u64 v[182:183], s[42:43], 0, v[134:135]
	s_mov_b32 m0, s66
	ds_read_b128 v[202:205], v158 offset:16384
	ds_read_b128 v[206:209], v158 offset:17408
	ds_read_b128 v[210:213], v158 offset:18432
	ds_read_b128 v[214:217], v158 offset:19456
	ds_read_b128 v[218:221], v158 offset:20480
	ds_read_b128 v[222:225], v158 offset:21504
	ds_read_b128 v[226:229], v158 offset:22528
	ds_read_b128 v[230:233], v158 offset:23552
	global_load_lds_dwordx4 v[182:183], off
	s_add_i32 m0, s66, 0x2000
	s_add_u32 s66, s42, 0x40000
	v_lshl_add_u64 v[234:235], s[42:43], 0, v[130:131]
	s_addc_u32 s67, s43, 0
	s_add_i32 s68, s58, s46
	global_load_lds_dwordx4 v[234:235], off
	v_lshl_add_u64 v[236:237], s[66:67], 0, v[134:135]
	s_mov_b32 m0, s68
	v_lshl_add_u64 v[238:239], s[44:45], 0, v[132:133]
	global_load_lds_dwordx4 v[236:237], off
	v_lshl_add_u64 v[236:237], s[66:67], 0, v[130:131]
	s_add_i32 m0, s68, 0x2000
	s_nop 0
	global_load_lds_dwordx4 v[236:237], off
	v_lshl_add_u64 v[236:237], s[44:45], 0, v[136:137]
	s_mov_b32 m0, s49
	s_nop 0
	global_load_lds_dwordx4 v[236:237], off
	s_mov_b32 m0, s50
	s_nop 0
	global_load_lds_dwordx4 v[238:239], off
	s_waitcnt vmcnt(8)
	s_waitcnt lgkmcnt(0)
	s_barrier
; #define PG8_STAGE(bufoff, gbase, voff) do { _Pragma("unroll") for (int _i = 0; _i < 2; ++_i) \
;         __builtin_amdgcn_global_load_lds((const unsigned*)((const char*)(gbase) + (voff)[_i]), (LAS unsigned*)(lds + (bufoff) + ldsw + _i * 8192), 16, 0, 0); } while (0)
; #define PG8_LDA(dst, b, h) do { _Pragma("unroll") for (int m = 0; m < 4; ++m) _Pragma("unroll") for (int k = 0; k < 2; ++k) dst[m][k] = *(const LAS bf16x8*)(lds + PG8_SA(b, h) + aoff + m * 2048 + k * 1024); } while (0)
; #define PG8_LDB(dst, b, h) do { _Pragma("unroll") for (int n = 0; n < 2; ++n) _Pragma("unroll") for (int k = 0; k < 2; ++k) dst[n][k] = *(const LAS bf16x8*)(lds + PG8_SB(b, h) + boff + n * 2048 + k * 1024); } while (0)
; #define PG8_MMA(ai, bj, At, Bt) do { __builtin_amdgcn_s_setprio(1); _Pragma("unroll") for (int m = 0; m < 4; ++m) _Pragma("unroll") for (int n = 0; n < 2; ++n) _Pragma("unroll") for (int k = 0; k < 2; ++k) \
;         acc[ai][bj][m][n] = __builtin_amdgcn_mfma_f32_16x16x32_bf16(Bt[n][k], At[m][k], acc[ai][bj][m][n], 0, 0, 0); __builtin_amdgcn_s_setprio(0); } while (0)
; #define PG8_WAIT_V(n) asm volatile("s_waitcnt vmcnt(" #n ")" ::: "memory")
; #define PG8_WAIT_L(n) asm volatile("s_waitcnt lgkmcnt(" #n ")" ::: "memory")
; #define PG8_BAR __builtin_amdgcn_s_barrier()
; #define PG8_SCHED __builtin_amdgcn_sched_barrier(0)
; template <class Epi, class Sched>
; DI void gemm_phase(LAS unsigned char* lds, const Gemm g, const Sched& S, const Epi& E) {
;     ...
;             PG8_WAIT_V(8); PG8_WAIT_L(0); PG8_BAR; PG8_MMA(1, 0, At, B0); PG8_MMA(1, 1, At, B1); PG8_BAR; PG8_SCHED;
;             PG8_LDB(B0, 1, 0); PG8_LDB(B1, 1, 1); PG8_SCHED; PG8_LDA(At, 1, 0); PG8_STAGE(PG8_SA(0, 1), a2 + hstepA, voffA);
;             PG8_WAIT_V(8); PG8_WAIT_L(0); PG8_BAR; PG8_MMA(0, 0, At, B0); PG8_MMA(0, 1, At, B1); PG8_BAR; PG8_SCHED;
	s_setprio 1
	v_mfma_f32_16x16x32_bf16 v[62:65], v[166:169], v[202:205], v[62:65]
	v_mfma_f32_16x16x32_bf16 v[54:57], v[174:177], v[202:205], v[54:57]
	v_mfma_f32_16x16x32_bf16 v[46:49], v[166:169], v[210:213], v[46:49]
	v_mfma_f32_16x16x32_bf16 v[38:41], v[174:177], v[210:213], v[38:41]
	v_mfma_f32_16x16x32_bf16 v[30:33], v[166:169], v[218:221], v[30:33]
	v_mfma_f32_16x16x32_bf16 v[22:25], v[174:177], v[218:221], v[22:25]
	v_mfma_f32_16x16x32_bf16 v[14:17], v[166:169], v[226:229], v[14:17]
	v_mfma_f32_16x16x32_bf16 v[6:9], v[174:177], v[226:229], v[6:9]
	v_mfma_f32_16x16x32_bf16 v[62:65], v[170:173], v[206:209], v[62:65]
	v_mfma_f32_16x16x32_bf16 v[54:57], v[178:181], v[206:209], v[54:57]
	v_mfma_f32_16x16x32_bf16 v[46:49], v[170:173], v[214:217], v[46:49]
	v_mfma_f32_16x16x32_bf16 v[38:41], v[178:181], v[214:217], v[38:41]
	v_mfma_f32_16x16x32_bf16 v[30:33], v[170:173], v[222:225], v[30:33]
	v_mfma_f32_16x16x32_bf16 v[22:25], v[178:181], v[222:225], v[22:25]
	v_mfma_f32_16x16x32_bf16 v[14:17], v[170:173], v[230:233], v[14:17]
	v_mfma_f32_16x16x32_bf16 v[6:9], v[178:181], v[230:233], v[6:9]
	v_mfma_f32_16x16x32_bf16 v[58:61], v[186:189], v[202:205], v[58:61]
	v_mfma_f32_16x16x32_bf16 v[50:53], v[194:197], v[202:205], v[50:53]
	v_mfma_f32_16x16x32_bf16 v[42:45], v[186:189], v[210:213], v[42:45]
	v_mfma_f32_16x16x32_bf16 v[34:37], v[194:197], v[210:213], v[34:37]
	v_mfma_f32_16x16x32_bf16 v[26:29], v[186:189], v[218:221], v[26:29]
	v_mfma_f32_16x16x32_bf16 v[18:21], v[194:197], v[218:221], v[18:21]
	v_mfma_f32_16x16x32_bf16 v[10:13], v[186:189], v[226:229], v[10:13]
	v_mfma_f32_16x16x32_bf16 v[2:5], v[194:197], v[226:229], v[2:5]
	v_mfma_f32_16x16x32_bf16 v[58:61], v[190:193], v[206:209], v[58:61]
	v_mfma_f32_16x16x32_bf16 v[50:53], v[198:201], v[206:209], v[50:53]
	v_mfma_f32_16x16x32_bf16 v[42:45], v[190:193], v[214:217], v[42:45]
	v_mfma_f32_16x16x32_bf16 v[34:37], v[198:201], v[214:217], v[34:37]
	v_mfma_f32_16x16x32_bf16 v[26:29], v[190:193], v[222:225], v[26:29]
	v_mfma_f32_16x16x32_bf16 v[18:21], v[198:201], v[222:225], v[18:21]
	v_mfma_f32_16x16x32_bf16 v[10:13], v[190:193], v[230:233], v[10:13]
	v_mfma_f32_16x16x32_bf16 v[2:5], v[198:201], v[230:233], v[2:5]
	s_setprio 0
	s_barrier
	s_add_i32 s66, 0, 0x18000
	v_add_u32_e32 v165, s66, v156
	s_add_i32 s67, 0, 0x1c000
	ds_read_b128 v[166:169], v165
	ds_read_b128 v[170:173], v165 offset:1024
	ds_read_b128 v[174:177], v165 offset:2048
	ds_read_b128 v[178:181], v165 offset:3072
	v_add_u32_e32 v165, s67, v156
	ds_read_b128 v[186:189], v165
	ds_read_b128 v[190:193], v165 offset:1024
	ds_read_b128 v[194:197], v165 offset:2048
	ds_read_b128 v[198:201], v165 offset:3072
	s_add_u32 s44, s44, 0x40000
	s_addc_u32 s45, s45, 0
	s_mov_b32 m0, s51
	v_lshl_add_u64 v[240:241], s[44:45], 0, v[136:137]
	ds_read_b128 v[202:205], v158 offset:32768
	ds_read_b128 v[206:209], v158 offset:33792
	ds_read_b128 v[210:213], v158 offset:34816
	ds_read_b128 v[214:217], v158 offset:35840
	ds_read_b128 v[218:221], v158 offset:36864
	ds_read_b128 v[222:225], v158 offset:37888
	ds_read_b128 v[226:229], v158 offset:38912
	ds_read_b128 v[230:233], v158 offset:39936
	global_load_lds_dwordx4 v[240:241], off
	v_lshl_add_u64 v[240:241], s[44:45], 0, v[132:133]
	s_mov_b32 m0, s52
	s_nop 0
	global_load_lds_dwordx4 v[240:241], off
	s_waitcnt vmcnt(8)
	s_waitcnt lgkmcnt(0)
	s_barrier
	s_setprio 1
	v_mfma_f32_16x16x32_bf16 v[126:129], v[166:169], v[202:205], v[126:129]
	v_mfma_f32_16x16x32_bf16 v[118:121], v[174:177], v[202:205], v[118:121]
	v_mfma_f32_16x16x32_bf16 v[110:113], v[166:169], v[210:213], v[110:113]
	v_mfma_f32_16x16x32_bf16 v[102:105], v[174:177], v[210:213], v[102:105]
	v_mfma_f32_16x16x32_bf16 v[94:97], v[166:169], v[218:221], v[94:97]
	v_mfma_f32_16x16x32_bf16 v[86:89], v[174:177], v[218:221], v[86:89]
	v_mfma_f32_16x16x32_bf16 v[78:81], v[166:169], v[226:229], v[78:81]
	v_mfma_f32_16x16x32_bf16 v[70:73], v[174:177], v[226:229], v[70:73]
	v_mfma_f32_16x16x32_bf16 v[126:129], v[170:173], v[206:209], v[126:129]
	v_mfma_f32_16x16x32_bf16 v[118:121], v[178:181], v[206:209], v[118:121]
	v_mfma_f32_16x16x32_bf16 v[110:113], v[170:173], v[214:217], v[110:113]
	v_mfma_f32_16x16x32_bf16 v[102:105], v[178:181], v[214:217], v[102:105]
	v_mfma_f32_16x16x32_bf16 v[94:97], v[170:173], v[222:225], v[94:97]
	v_mfma_f32_16x16x32_bf16 v[86:89], v[178:181], v[222:225], v[86:89]
	v_mfma_f32_16x16x32_bf16 v[78:81], v[170:173], v[230:233], v[78:81]
	v_mfma_f32_16x16x32_bf16 v[70:73], v[178:181], v[230:233], v[70:73]
	v_mfma_f32_16x16x32_bf16 v[122:125], v[186:189], v[202:205], v[122:125]
	v_mfma_f32_16x16x32_bf16 v[114:117], v[194:197], v[202:205], v[114:117]
	v_mfma_f32_16x16x32_bf16 v[106:109], v[186:189], v[210:213], v[106:109]
	v_mfma_f32_16x16x32_bf16 v[98:101], v[194:197], v[210:213], v[98:101]
	v_mfma_f32_16x16x32_bf16 v[90:93], v[186:189], v[218:221], v[90:93]
	v_mfma_f32_16x16x32_bf16 v[82:85], v[194:197], v[218:221], v[82:85]
	v_mfma_f32_16x16x32_bf16 v[74:77], v[186:189], v[226:229], v[74:77]
	v_mfma_f32_16x16x32_bf16 v[66:69], v[194:197], v[226:229], v[66:69]
	v_mfma_f32_16x16x32_bf16 v[122:125], v[190:193], v[206:209], v[122:125]
	v_mfma_f32_16x16x32_bf16 v[114:117], v[198:201], v[206:209], v[114:117]
	v_mfma_f32_16x16x32_bf16 v[106:109], v[190:193], v[214:217], v[106:109]
	v_mfma_f32_16x16x32_bf16 v[98:101], v[198:201], v[214:217], v[98:101]
	v_mfma_f32_16x16x32_bf16 v[90:93], v[190:193], v[222:225], v[90:93]
	v_mfma_f32_16x16x32_bf16 v[82:85], v[198:201], v[222:225], v[82:85]
	v_mfma_f32_16x16x32_bf16 v[74:77], v[190:193], v[230:233], v[74:77]
	v_mfma_f32_16x16x32_bf16 v[66:69], v[198:201], v[230:233], v[66:69]
	s_setprio 0
	s_barrier
; DI float fast_exp2(float x) { return __builtin_amdgcn_exp2f(x); }
; DI float fast_rcp(float x) { return __builtin_amdgcn_rcpf(x); }
; #define PG8_STAGE(bufoff, gbase, voff) do { _Pragma("unroll") for (int _i = 0; _i < 2; ++_i) \
;         __builtin_amdgcn_global_load_lds((const unsigned*)((const char*)(gbase) + (voff)[_i]), (LAS unsigned*)(lds + (bufoff) + ldsw + _i * 8192), 16, 0, 0); } while (0)
; #define PG8_LDA(dst, b, h) do { _Pragma("unroll") for (int m = 0; m < 4; ++m) _Pragma("unroll") for (int k = 0; k < 2; ++k) dst[m][k] = *(const LAS bf16x8*)(lds + PG8_SA(b, h) + aoff + m * 2048 + k * 1024); } while (0)
; #define PG8_MMA(ai, bj, At, Bt) do { __builtin_amdgcn_s_setprio(1); _Pragma("unroll") for (int m = 0; m < 4; ++m) _Pragma("unroll") for (int n = 0; n < 2; ++n) _Pragma("unroll") for (int k = 0; k < 2; ++k) \
;         acc[ai][bj][m][n] = __builtin_amdgcn_mfma_f32_16x16x32_bf16(Bt[n][k], At[m][k], acc[ai][bj][m][n], 0, 0, 0); __builtin_amdgcn_s_setprio(0); } while (0)
; #define PG8_WAIT_V(n) asm volatile("s_waitcnt vmcnt(" #n ")" ::: "memory")
; #define PG8_WAIT_L(n) asm volatile("s_waitcnt lgkmcnt(" #n ")" ::: "memory")
; #define PG8_BAR __builtin_amdgcn_s_barrier()
; template <class Epi, class Sched>
; DI void gemm_phase(LAS unsigned char* lds, const Gemm g, const Sched& S, const Epi& E) {
;     ...
;             PG8_LDA(At, 1, 1); PG8_STAGE(PG8_SB(1, 0), b3, voffB); PG8_STAGE(PG8_SB(1, 1), b3 + hstepB, voffB); PG8_STAGE(PG8_SA(1, 0), a3, voffA);
;             PG8_WAIT_V(8); PG8_WAIT_L(0); PG8_BAR; PG8_MMA(1, 0, At, B0); PG8_MMA(1, 1, At, B1); PG8_BAR; PG8_SCHED;
;         }
;         if (wr == 0) PG8_BAR;
;     DI void operator()(Acc& acc, const pg8::Unit& u, int wr, int wc, int fr, int fq, const Pre& pr) const {
;     ...
;                 const int row = u.pm * 256 + ai * 128 + wr * 64 + m * 16 + fr;
;                 const float msq = msq_of(pr.v[ai * 4 + m]), nrl = -1.4426950408889634f * __builtin_amdgcn_rsqf(msq);
;                 f32x4 h[2];
; #pragma unroll
;                 for (int n = 0; n < 2; ++n)
; #pragma unroll
;                     for (int i = 0; i < 4; ++i) { const float ga = acc[ai][0][m][n][i], ua = acc[ai][1][m][n][i];
;                         const float e = fast_exp2(ga * nrl); h[n][i] = (ga * ua) * fast_rcp(__builtin_fmaf(e, msq, msq)); }
;                 store8(H + (size_t)row * FF + col, h[0], h[1]);
	s_add_i32 s44, s66, s46
	v_lshl_add_u64 v[182:183], v[182:183], 0, s[16:17]
	s_mov_b32 m0, s44
	ds_read_b128 v[202:205], v158 offset:49152
	ds_read_b128 v[206:209], v158 offset:50176
	ds_read_b128 v[210:213], v158 offset:51200
	ds_read_b128 v[214:217], v158 offset:52224
	ds_read_b128 v[218:221], v158 offset:53248
	ds_read_b128 v[222:225], v158 offset:54272
	ds_read_b128 v[226:229], v158 offset:55296
	ds_read_b128 v[230:233], v158 offset:56320
	global_load_lds_dwordx4 v[182:183], off
	s_add_i32 m0, s44, 0x2000
	s_add_u32 s42, s42, 0x40080
	v_lshl_add_u64 v[182:183], v[234:235], 0, s[16:17]
	s_addc_u32 s43, s43, 0
	s_add_i32 s44, s67, s46
	global_load_lds_dwordx4 v[182:183], off
	v_lshl_add_u64 v[182:183], s[42:43], 0, v[134:135]
	s_mov_b32 m0, s44
	s_nop 0
	global_load_lds_dwordx4 v[182:183], off
	v_lshl_add_u64 v[182:183], s[42:43], 0, v[130:131]
	s_add_i32 m0, s44, 0x2000
	s_nop 0
	global_load_lds_dwordx4 v[182:183], off
	v_lshl_add_u64 v[182:183], v[236:237], 0, s[16:17]
	s_mov_b32 m0, s54
	s_nop 0
	global_load_lds_dwordx4 v[182:183], off
	v_lshl_add_u64 v[182:183], v[238:239], 0, s[16:17]
	s_mov_b32 m0, s55
	s_nop 0
	global_load_lds_dwordx4 v[182:183], off
	s_waitcnt vmcnt(8)
	s_waitcnt lgkmcnt(0)
	s_barrier
	s_setprio 1
	v_mfma_f32_16x16x32_bf16 v[62:65], v[166:169], v[202:205], v[62:65]
	v_mfma_f32_16x16x32_bf16 v[54:57], v[174:177], v[202:205], v[54:57]
	v_mfma_f32_16x16x32_bf16 v[46:49], v[166:169], v[210:213], v[46:49]
	v_mfma_f32_16x16x32_bf16 v[38:41], v[174:177], v[210:213], v[38:41]
	v_mfma_f32_16x16x32_bf16 v[30:33], v[166:169], v[218:221], v[30:33]
	v_mfma_f32_16x16x32_bf16 v[22:25], v[174:177], v[218:221], v[22:25]
	v_mfma_f32_16x16x32_bf16 v[14:17], v[166:169], v[226:229], v[14:17]
	v_mfma_f32_16x16x32_bf16 v[6:9], v[174:177], v[226:229], v[6:9]
	v_mfma_f32_16x16x32_bf16 v[62:65], v[170:173], v[206:209], v[62:65]
	v_mfma_f32_16x16x32_bf16 v[54:57], v[178:181], v[206:209], v[54:57]
	v_mfma_f32_16x16x32_bf16 v[46:49], v[170:173], v[214:217], v[46:49]
	v_mfma_f32_16x16x32_bf16 v[38:41], v[178:181], v[214:217], v[38:41]
	v_mfma_f32_16x16x32_bf16 v[30:33], v[170:173], v[222:225], v[30:33]
	v_mfma_f32_16x16x32_bf16 v[22:25], v[178:181], v[222:225], v[22:25]
	v_mfma_f32_16x16x32_bf16 v[14:17], v[170:173], v[230:233], v[14:17]
	v_mfma_f32_16x16x32_bf16 v[6:9], v[178:181], v[230:233], v[6:9]
	v_mfma_f32_16x16x32_bf16 v[58:61], v[186:189], v[202:205], v[58:61]
	v_mfma_f32_16x16x32_bf16 v[50:53], v[194:197], v[202:205], v[50:53]
	v_mfma_f32_16x16x32_bf16 v[42:45], v[186:189], v[210:213], v[42:45]
	v_mfma_f32_16x16x32_bf16 v[34:37], v[194:197], v[210:213], v[34:37]
	v_mfma_f32_16x16x32_bf16 v[26:29], v[186:189], v[218:221], v[26:29]
	v_mfma_f32_16x16x32_bf16 v[18:21], v[194:197], v[218:221], v[18:21]
	v_mfma_f32_16x16x32_bf16 v[10:13], v[186:189], v[226:229], v[10:13]
	v_mfma_f32_16x16x32_bf16 v[2:5], v[194:197], v[226:229], v[2:5]
	v_mfma_f32_16x16x32_bf16 v[58:61], v[190:193], v[206:209], v[58:61]
	v_mfma_f32_16x16x32_bf16 v[50:53], v[198:201], v[206:209], v[50:53]
	v_mfma_f32_16x16x32_bf16 v[42:45], v[190:193], v[214:217], v[42:45]
	v_mfma_f32_16x16x32_bf16 v[34:37], v[198:201], v[214:217], v[34:37]
	v_mfma_f32_16x16x32_bf16 v[26:29], v[190:193], v[222:225], v[26:29]
	v_mfma_f32_16x16x32_bf16 v[18:21], v[198:201], v[222:225], v[18:21]
	v_mfma_f32_16x16x32_bf16 v[10:13], v[190:193], v[230:233], v[10:13]
	v_mfma_f32_16x16x32_bf16 v[2:5], v[198:201], v[230:233], v[2:5]
	s_setprio 0
	s_barrier
	s_add_i32 s65, s65, 2
	s_add_u32 s40, s40, 0x100
	s_addc_u32 s41, s41, 0
	s_add_u32 s63, s63, 0x100
	s_addc_u32 s64, s64, 0
	s_cmp_gt_u32 s65, 13
	s_cbranch_scc0 .LBB0_1234
	s_mov_b32 s99, 1
	s_and_b64 vcc, exec, s[18:19]
	s_cbranch_vccz .LBB0_1237
	s_barrier
.LBB0_1237:
	v_fmamk_f32 v186, v164, 0x3a800000, v159
	v_rsq_f32_e32 v189, v186
	v_lshl_or_b32 v202, s60, 7, v157
	v_lshlrev_b32_e32 v202, 1, v202
	v_mad_u32_u24 v194, v154, s59, v202
	v_mul_f32_e32 v188, 0xbfb8aa3b, v189
	v_fmamk_f32 v190, v163, 0x3a800000, v159
	v_rsq_f32_e32 v193, v190
	v_add_u32_e32 v195, 0x16000, v194
	v_add_u32_e32 v196, 0x2c000, v194
	v_add_u32_e32 v197, 0x42000, v194
	v_add_u32_e32 v198, 0xb0000, v194
	v_add_u32_e32 v199, 0xc6000, v194
	v_add_u32_e32 v200, 0xdc000, v194
	v_add_u32_e32 v201, 0xf2000, v194
	v_mul_f32_e32 v192, 0xbfb8aa3b, v193
	v_pk_mul_f32 v[122:123], v[126:127], v[122:123]
	v_pk_mul_f32 v[124:125], v[128:129], v[124:125]
	v_pk_mul_f32 v[114:115], v[118:119], v[114:115]
	v_pk_mul_f32 v[116:117], v[120:121], v[116:117]
	v_pk_mul_f32 v[126:127], v[126:127], v[188:189] op_sel_hi:[1,0]
	v_pk_mul_f32 v[128:129], v[128:129], v[188:189] op_sel_hi:[1,0]
	v_pk_mul_f32 v[118:119], v[118:119], v[188:189] op_sel_hi:[1,0]
	v_pk_mul_f32 v[120:121], v[120:121], v[188:189] op_sel_hi:[1,0]
	v_exp_f32_e32 v126, v126
	v_exp_f32_e32 v127, v127
	v_exp_f32_e32 v128, v128
	v_exp_f32_e32 v129, v129
	v_exp_f32_e32 v118, v118
	v_exp_f32_e32 v119, v119
	v_exp_f32_e32 v120, v120
	v_exp_f32_e32 v121, v121
	v_pk_fma_f32 v[126:127], v[126:127], v[186:187], v[186:187] op_sel_hi:[1,0,0]
	v_pk_fma_f32 v[128:129], v[128:129], v[186:187], v[186:187] op_sel_hi:[1,0,0]
	v_pk_fma_f32 v[118:119], v[118:119], v[186:187], v[186:187] op_sel_hi:[1,0,0]
	v_pk_fma_f32 v[120:121], v[120:121], v[186:187], v[186:187] op_sel_hi:[1,0,0]
	v_rcp_f32_e32 v126, v126
	v_rcp_f32_e32 v127, v127
	v_rcp_f32_e32 v128, v128
	v_rcp_f32_e32 v129, v129
	v_rcp_f32_e32 v118, v118
	v_rcp_f32_e32 v119, v119
	v_rcp_f32_e32 v120, v120
	v_rcp_f32_e32 v121, v121
	v_fmamk_f32 v186, v162, 0x3a800000, v159
	v_rsq_f32_e32 v189, v186
	v_pk_mul_f32 v[122:123], v[126:127], v[122:123]
	v_pk_mul_f32 v[124:125], v[128:129], v[124:125]
; DI float fast_exp2(float x) { return __builtin_amdgcn_exp2f(x); }
; DI float fast_rcp(float x) { return __builtin_amdgcn_rcpf(x); }
;     DI void operator()(Acc& acc, const pg8::Unit& u, int wr, int wc, int fr, int fq, const Pre& pr) const {
;     ...
;                 const float msq = msq_of(pr.v[ai * 4 + m]), nrl = -1.4426950408889634f * __builtin_amdgcn_rsqf(msq);
;                 f32x4 h[2];
; #pragma unroll
;                 for (int n = 0; n < 2; ++n)
; #pragma unroll
;                     for (int i = 0; i < 4; ++i) { const float ga = acc[ai][0][m][n][i], ua = acc[ai][1][m][n][i];
;                         const float e = fast_exp2(ga * nrl); h[n][i] = (ga * ua) * fast_rcp(__builtin_fmaf(e, msq, msq)); }
;                 store8(H + (size_t)row * FF + col, h[0], h[1]);
	v_pk_mul_f32 v[114:115], v[118:119], v[114:115]
	v_pk_mul_f32 v[116:117], v[120:121], v[116:117]
	v_cvt_pk_bf16_f32 v126, v122, v123
	v_cvt_pk_bf16_f32 v127, v124, v125
	v_cvt_pk_bf16_f32 v128, v114, v115
	v_cvt_pk_bf16_f32 v129, v116, v117
	v_mul_f32_e32 v188, 0xbfb8aa3b, v189
	v_pk_mul_f32 v[106:107], v[110:111], v[106:107]
	v_pk_mul_f32 v[108:109], v[112:113], v[108:109]
	v_pk_mul_f32 v[98:99], v[102:103], v[98:99]
	v_pk_mul_f32 v[100:101], v[104:105], v[100:101]
	v_pk_mul_f32 v[110:111], v[110:111], v[192:193] op_sel_hi:[1,0]
	v_pk_mul_f32 v[112:113], v[112:113], v[192:193] op_sel_hi:[1,0]
	v_pk_mul_f32 v[102:103], v[102:103], v[192:193] op_sel_hi:[1,0]
	v_pk_mul_f32 v[104:105], v[104:105], v[192:193] op_sel_hi:[1,0]
	v_exp_f32_e32 v110, v110
	v_exp_f32_e32 v111, v111
	v_exp_f32_e32 v112, v112
	v_exp_f32_e32 v113, v113
	v_exp_f32_e32 v102, v102
	v_exp_f32_e32 v103, v103
	v_exp_f32_e32 v104, v104
	v_exp_f32_e32 v105, v105
	global_store_dwordx4 v194, v[126:129], s[12:13]
	v_pk_fma_f32 v[110:111], v[110:111], v[190:191], v[190:191] op_sel_hi:[1,0,0]
	v_pk_fma_f32 v[112:113], v[112:113], v[190:191], v[190:191] op_sel_hi:[1,0,0]
	v_pk_fma_f32 v[102:103], v[102:103], v[190:191], v[190:191] op_sel_hi:[1,0,0]
	v_pk_fma_f32 v[104:105], v[104:105], v[190:191], v[190:191] op_sel_hi:[1,0,0]
	v_rcp_f32_e32 v110, v110
	v_rcp_f32_e32 v111, v111
	v_rcp_f32_e32 v112, v112
	v_rcp_f32_e32 v113, v113
	v_rcp_f32_e32 v102, v102
	v_rcp_f32_e32 v103, v103
	v_rcp_f32_e32 v104, v104
	v_rcp_f32_e32 v105, v105
	v_fmamk_f32 v190, v155, 0x3a800000, v159
	v_rsq_f32_e32 v193, v190
	v_pk_mul_f32 v[106:107], v[110:111], v[106:107]
	v_pk_mul_f32 v[108:109], v[112:113], v[108:109]
	v_pk_mul_f32 v[98:99], v[102:103], v[98:99]
	v_pk_mul_f32 v[100:101], v[104:105], v[100:101]
	v_cvt_pk_bf16_f32 v110, v106, v107
	v_cvt_pk_bf16_f32 v111, v108, v109
	v_cvt_pk_bf16_f32 v112, v98, v99
	v_cvt_pk_bf16_f32 v113, v100, v101
	v_mul_f32_e32 v192, 0xbfb8aa3b, v193
	v_pk_mul_f32 v[90:91], v[94:95], v[90:91]
	v_pk_mul_f32 v[92:93], v[96:97], v[92:93]
	v_pk_mul_f32 v[82:83], v[86:87], v[82:83]
	v_pk_mul_f32 v[84:85], v[88:89], v[84:85]
	v_pk_mul_f32 v[94:95], v[94:95], v[188:189] op_sel_hi:[1,0]
	v_pk_mul_f32 v[96:97], v[96:97], v[188:189] op_sel_hi:[1,0]
	v_pk_mul_f32 v[86:87], v[86:87], v[188:189] op_sel_hi:[1,0]
	v_pk_mul_f32 v[88:89], v[88:89], v[188:189] op_sel_hi:[1,0]
	v_exp_f32_e32 v94, v94
	v_exp_f32_e32 v95, v95
	v_exp_f32_e32 v96, v96
	v_exp_f32_e32 v97, v97
	v_exp_f32_e32 v86, v86
	v_exp_f32_e32 v87, v87
	v_exp_f32_e32 v88, v88
	v_exp_f32_e32 v89, v89
	global_store_dwordx4 v195, v[110:113], s[12:13]
	v_pk_fma_f32 v[94:95], v[94:95], v[186:187], v[186:187] op_sel_hi:[1,0,0]
	v_pk_fma_f32 v[96:97], v[96:97], v[186:187], v[186:187] op_sel_hi:[1,0,0]
	v_pk_fma_f32 v[86:87], v[86:87], v[186:187], v[186:187] op_sel_hi:[1,0,0]
	v_pk_fma_f32 v[88:89], v[88:89], v[186:187], v[186:187] op_sel_hi:[1,0,0]
	v_rcp_f32_e32 v94, v94
	v_rcp_f32_e32 v95, v95
	v_rcp_f32_e32 v96, v96
	v_rcp_f32_e32 v97, v97
	v_rcp_f32_e32 v86, v86
	v_rcp_f32_e32 v87, v87
	v_rcp_f32_e32 v88, v88
	v_rcp_f32_e32 v89, v89
	v_fmamk_f32 v186, v153, 0x3a800000, v159
	v_rsq_f32_e32 v189, v186
	v_pk_mul_f32 v[90:91], v[94:95], v[90:91]
	v_pk_mul_f32 v[92:93], v[96:97], v[92:93]
	v_pk_mul_f32 v[82:83], v[86:87], v[82:83]
	v_pk_mul_f32 v[84:85], v[88:89], v[84:85]
	v_cvt_pk_bf16_f32 v94, v90, v91
	v_cvt_pk_bf16_f32 v95, v92, v93
	v_cvt_pk_bf16_f32 v96, v82, v83
	v_cvt_pk_bf16_f32 v97, v84, v85
	v_mul_f32_e32 v188, 0xbfb8aa3b, v189
	v_pk_mul_f32 v[74:75], v[78:79], v[74:75]
	v_pk_mul_f32 v[76:77], v[80:81], v[76:77]
	v_pk_mul_f32 v[66:67], v[70:71], v[66:67]
	v_pk_mul_f32 v[68:69], v[72:73], v[68:69]
	v_pk_mul_f32 v[78:79], v[78:79], v[192:193] op_sel_hi:[1,0]
	v_pk_mul_f32 v[80:81], v[80:81], v[192:193] op_sel_hi:[1,0]
	v_pk_mul_f32 v[70:71], v[70:71], v[192:193] op_sel_hi:[1,0]
	v_pk_mul_f32 v[72:73], v[72:73], v[192:193] op_sel_hi:[1,0]
	v_exp_f32_e32 v78, v78
	v_exp_f32_e32 v79, v79
	v_exp_f32_e32 v80, v80
	v_exp_f32_e32 v81, v81
	v_exp_f32_e32 v70, v70
	v_exp_f32_e32 v71, v71
	v_exp_f32_e32 v72, v72
	v_exp_f32_e32 v73, v73
	global_store_dwordx4 v196, v[94:97], s[12:13]
	v_pk_fma_f32 v[78:79], v[78:79], v[190:191], v[190:191] op_sel_hi:[1,0,0]
	v_pk_fma_f32 v[80:81], v[80:81], v[190:191], v[190:191] op_sel_hi:[1,0,0]
	v_pk_fma_f32 v[70:71], v[70:71], v[190:191], v[190:191] op_sel_hi:[1,0,0]
	v_pk_fma_f32 v[72:73], v[72:73], v[190:191], v[190:191] op_sel_hi:[1,0,0]
	v_rcp_f32_e32 v78, v78
	v_rcp_f32_e32 v79, v79
	v_rcp_f32_e32 v80, v80
	v_rcp_f32_e32 v81, v81
	v_rcp_f32_e32 v70, v70
	v_rcp_f32_e32 v71, v71
	v_rcp_f32_e32 v72, v72
	v_rcp_f32_e32 v73, v73
	v_fmamk_f32 v190, v151, 0x3a800000, v159
	v_rsq_f32_e32 v193, v190
	v_pk_mul_f32 v[74:75], v[78:79], v[74:75]
	v_pk_mul_f32 v[76:77], v[80:81], v[76:77]
	v_pk_mul_f32 v[66:67], v[70:71], v[66:67]
	v_pk_mul_f32 v[68:69], v[72:73], v[68:69]
	v_cvt_pk_bf16_f32 v78, v74, v75
	v_cvt_pk_bf16_f32 v79, v76, v77
	v_cvt_pk_bf16_f32 v80, v66, v67
	v_cvt_pk_bf16_f32 v81, v68, v69
	v_mul_f32_e32 v192, 0xbfb8aa3b, v193
	v_pk_mul_f32 v[58:59], v[62:63], v[58:59]
	v_pk_mul_f32 v[60:61], v[64:65], v[60:61]
	v_pk_mul_f32 v[50:51], v[54:55], v[50:51]
	v_pk_mul_f32 v[52:53], v[56:57], v[52:53]
	v_pk_mul_f32 v[62:63], v[62:63], v[188:189] op_sel_hi:[1,0]
	v_pk_mul_f32 v[64:65], v[64:65], v[188:189] op_sel_hi:[1,0]
	v_pk_mul_f32 v[54:55], v[54:55], v[188:189] op_sel_hi:[1,0]
	v_pk_mul_f32 v[56:57], v[56:57], v[188:189] op_sel_hi:[1,0]
	v_exp_f32_e32 v62, v62
	v_exp_f32_e32 v63, v63
	v_exp_f32_e32 v64, v64
	v_exp_f32_e32 v65, v65
	v_exp_f32_e32 v54, v54
	v_exp_f32_e32 v55, v55
; DI float fast_exp2(float x) { return __builtin_amdgcn_exp2f(x); }
; DI float fast_rcp(float x) { return __builtin_amdgcn_rcpf(x); }
; #define PG8_BAR __builtin_amdgcn_s_barrier()
; template <class Epi, class Sched>
; DI void gemm_phase(LAS unsigned char* lds, const Gemm g, const Sched& S, const Epi& E) {
;     ...
;         if (!has_next) break;
;         if (!(Epi::CHAIN && cur.src == 0)) {
; #pragma unroll
;             for (int a = 0; a < 2; ++a)
; #pragma unroll
;                 for (int b = 0; b < 2; ++b)
; #pragma unroll
;                     for (int m = 0; m < 4; ++m)
; #pragma unroll
;                         for (int n = 0; n < 2; ++n) acc[a][b][m][n] = (f32x4){0.f, 0.f, 0.f, 0.f};
;         }
;         cur = nxt; cA = nA; cB = nB; ++ui;
;         if (wr == 1) PG8_BAR;
;     DI void operator()(Acc& acc, const pg8::Unit& u, int wr, int wc, int fr, int fq, const Pre& pr) const {
;     ...
;                 const float msq = msq_of(pr.v[ai * 4 + m]), nrl = -1.4426950408889634f * __builtin_amdgcn_rsqf(msq);
;                 f32x4 h[2];
; #pragma unroll
;                 for (int n = 0; n < 2; ++n)
; #pragma unroll
;                     for (int i = 0; i < 4; ++i) { const float ga = acc[ai][0][m][n][i], ua = acc[ai][1][m][n][i];
;                         const float e = fast_exp2(ga * nrl); h[n][i] = (ga * ua) * fast_rcp(__builtin_fmaf(e, msq, msq)); }
;                 store8(H + (size_t)row * FF + col, h[0], h[1]);
	v_exp_f32_e32 v56, v56
	v_exp_f32_e32 v57, v57
	global_store_dwordx4 v197, v[78:81], s[12:13]
	v_pk_fma_f32 v[62:63], v[62:63], v[186:187], v[186:187] op_sel_hi:[1,0,0]
	v_pk_fma_f32 v[64:65], v[64:65], v[186:187], v[186:187] op_sel_hi:[1,0,0]
	v_pk_fma_f32 v[54:55], v[54:55], v[186:187], v[186:187] op_sel_hi:[1,0,0]
	v_pk_fma_f32 v[56:57], v[56:57], v[186:187], v[186:187] op_sel_hi:[1,0,0]
	v_rcp_f32_e32 v62, v62
	v_rcp_f32_e32 v63, v63
	v_rcp_f32_e32 v64, v64
	v_rcp_f32_e32 v65, v65
	v_rcp_f32_e32 v54, v54
	v_rcp_f32_e32 v55, v55
	v_rcp_f32_e32 v56, v56
	v_rcp_f32_e32 v57, v57
	v_fmamk_f32 v186, v149, 0x3a800000, v159
	v_rsq_f32_e32 v189, v186
	v_pk_mul_f32 v[58:59], v[62:63], v[58:59]
	v_pk_mul_f32 v[60:61], v[64:65], v[60:61]
	v_pk_mul_f32 v[50:51], v[54:55], v[50:51]
	v_pk_mul_f32 v[52:53], v[56:57], v[52:53]
	v_cvt_pk_bf16_f32 v62, v58, v59
	v_cvt_pk_bf16_f32 v63, v60, v61
	v_cvt_pk_bf16_f32 v64, v50, v51
	v_cvt_pk_bf16_f32 v65, v52, v53
	v_mul_f32_e32 v188, 0xbfb8aa3b, v189
	v_pk_mul_f32 v[42:43], v[46:47], v[42:43]
	v_pk_mul_f32 v[44:45], v[48:49], v[44:45]
	v_pk_mul_f32 v[34:35], v[38:39], v[34:35]
	v_pk_mul_f32 v[36:37], v[40:41], v[36:37]
	v_pk_mul_f32 v[46:47], v[46:47], v[192:193] op_sel_hi:[1,0]
	v_pk_mul_f32 v[48:49], v[48:49], v[192:193] op_sel_hi:[1,0]
	v_pk_mul_f32 v[38:39], v[38:39], v[192:193] op_sel_hi:[1,0]
	v_pk_mul_f32 v[40:41], v[40:41], v[192:193] op_sel_hi:[1,0]
	v_exp_f32_e32 v46, v46
	v_exp_f32_e32 v47, v47
	v_exp_f32_e32 v48, v48
	v_exp_f32_e32 v49, v49
	v_exp_f32_e32 v38, v38
	v_exp_f32_e32 v39, v39
	v_exp_f32_e32 v40, v40
	v_exp_f32_e32 v41, v41
	global_store_dwordx4 v198, v[62:65], s[12:13]
	v_pk_fma_f32 v[46:47], v[46:47], v[190:191], v[190:191] op_sel_hi:[1,0,0]
	v_pk_fma_f32 v[48:49], v[48:49], v[190:191], v[190:191] op_sel_hi:[1,0,0]
	v_pk_fma_f32 v[38:39], v[38:39], v[190:191], v[190:191] op_sel_hi:[1,0,0]
	v_pk_fma_f32 v[40:41], v[40:41], v[190:191], v[190:191] op_sel_hi:[1,0,0]
	v_rcp_f32_e32 v46, v46
	v_rcp_f32_e32 v47, v47
	v_rcp_f32_e32 v48, v48
	v_rcp_f32_e32 v49, v49
	v_rcp_f32_e32 v38, v38
	v_rcp_f32_e32 v39, v39
	v_rcp_f32_e32 v40, v40
	v_rcp_f32_e32 v41, v41
	v_fmamk_f32 v190, v147, 0x3a800000, v159
	v_rsq_f32_e32 v193, v190
	v_pk_mul_f32 v[42:43], v[46:47], v[42:43]
	v_pk_mul_f32 v[44:45], v[48:49], v[44:45]
	v_pk_mul_f32 v[34:35], v[38:39], v[34:35]
	v_pk_mul_f32 v[36:37], v[40:41], v[36:37]
	v_cvt_pk_bf16_f32 v46, v42, v43
	v_cvt_pk_bf16_f32 v47, v44, v45
	v_cvt_pk_bf16_f32 v48, v34, v35
	v_cvt_pk_bf16_f32 v49, v36, v37
	v_mul_f32_e32 v192, 0xbfb8aa3b, v193
	v_pk_mul_f32 v[26:27], v[30:31], v[26:27]
	v_pk_mul_f32 v[28:29], v[32:33], v[28:29]
	v_pk_mul_f32 v[18:19], v[22:23], v[18:19]
	v_pk_mul_f32 v[20:21], v[24:25], v[20:21]
	v_pk_mul_f32 v[30:31], v[30:31], v[188:189] op_sel_hi:[1,0]
	v_pk_mul_f32 v[32:33], v[32:33], v[188:189] op_sel_hi:[1,0]
	v_pk_mul_f32 v[22:23], v[22:23], v[188:189] op_sel_hi:[1,0]
	v_pk_mul_f32 v[24:25], v[24:25], v[188:189] op_sel_hi:[1,0]
	v_exp_f32_e32 v30, v30
	v_exp_f32_e32 v31, v31
	v_exp_f32_e32 v32, v32
	v_exp_f32_e32 v33, v33
	v_exp_f32_e32 v22, v22
	v_exp_f32_e32 v23, v23
	v_exp_f32_e32 v24, v24
	v_exp_f32_e32 v25, v25
	global_store_dwordx4 v199, v[46:49], s[12:13]
	v_pk_fma_f32 v[30:31], v[30:31], v[186:187], v[186:187] op_sel_hi:[1,0,0]
	v_pk_fma_f32 v[32:33], v[32:33], v[186:187], v[186:187] op_sel_hi:[1,0,0]
	v_pk_fma_f32 v[22:23], v[22:23], v[186:187], v[186:187] op_sel_hi:[1,0,0]
	v_pk_fma_f32 v[24:25], v[24:25], v[186:187], v[186:187] op_sel_hi:[1,0,0]
	v_rcp_f32_e32 v30, v30
	v_rcp_f32_e32 v31, v31
	v_rcp_f32_e32 v32, v32
	v_rcp_f32_e32 v33, v33
	v_rcp_f32_e32 v22, v22
	v_rcp_f32_e32 v23, v23
	v_rcp_f32_e32 v24, v24
	v_rcp_f32_e32 v25, v25
	v_pk_mul_f32 v[26:27], v[30:31], v[26:27]
	v_pk_mul_f32 v[28:29], v[32:33], v[28:29]
	v_pk_mul_f32 v[18:19], v[22:23], v[18:19]
	v_pk_mul_f32 v[20:21], v[24:25], v[20:21]
	v_cvt_pk_bf16_f32 v30, v26, v27
	v_cvt_pk_bf16_f32 v31, v28, v29
	v_cvt_pk_bf16_f32 v32, v18, v19
	v_cvt_pk_bf16_f32 v33, v20, v21
	v_pk_mul_f32 v[10:11], v[14:15], v[10:11]
	v_pk_mul_f32 v[12:13], v[16:17], v[12:13]
	v_pk_mul_f32 v[2:3], v[6:7], v[2:3]
	v_pk_mul_f32 v[4:5], v[8:9], v[4:5]
	v_pk_mul_f32 v[14:15], v[14:15], v[192:193] op_sel_hi:[1,0]
	v_pk_mul_f32 v[16:17], v[16:17], v[192:193] op_sel_hi:[1,0]
	v_pk_mul_f32 v[6:7], v[6:7], v[192:193] op_sel_hi:[1,0]
	v_pk_mul_f32 v[8:9], v[8:9], v[192:193] op_sel_hi:[1,0]
	v_exp_f32_e32 v14, v14
	v_exp_f32_e32 v15, v15
	v_exp_f32_e32 v16, v16
	v_exp_f32_e32 v17, v17
	v_exp_f32_e32 v6, v6
	v_exp_f32_e32 v7, v7
	v_exp_f32_e32 v8, v8
	v_exp_f32_e32 v9, v9
	global_store_dwordx4 v200, v[30:33], s[12:13]
	v_pk_fma_f32 v[14:15], v[14:15], v[190:191], v[190:191] op_sel_hi:[1,0,0]
	v_pk_fma_f32 v[16:17], v[16:17], v[190:191], v[190:191] op_sel_hi:[1,0,0]
	v_pk_fma_f32 v[6:7], v[6:7], v[190:191], v[190:191] op_sel_hi:[1,0,0]
	v_pk_fma_f32 v[8:9], v[8:9], v[190:191], v[190:191] op_sel_hi:[1,0,0]
	v_rcp_f32_e32 v14, v14
	v_rcp_f32_e32 v15, v15
	v_rcp_f32_e32 v16, v16
	v_rcp_f32_e32 v17, v17
	v_rcp_f32_e32 v6, v6
	v_rcp_f32_e32 v7, v7
	v_rcp_f32_e32 v8, v8
	v_rcp_f32_e32 v9, v9
	v_pk_mul_f32 v[10:11], v[14:15], v[10:11]
	v_pk_mul_f32 v[12:13], v[16:17], v[12:13]
	v_pk_mul_f32 v[2:3], v[6:7], v[2:3]
	v_pk_mul_f32 v[4:5], v[8:9], v[4:5]
	v_cvt_pk_bf16_f32 v14, v10, v11
	v_cvt_pk_bf16_f32 v15, v12, v13
	v_cvt_pk_bf16_f32 v16, v2, v3
	v_cvt_pk_bf16_f32 v17, v4, v5
	s_waitcnt vmcnt(7)
	s_andn2_b64 vcc, exec, s[4:5]
	s_mov_b64 s[4:5], -1
	global_store_dwordx4 v201, v[14:17], s[12:13]
	s_cbranch_vccnz .LBB0_1230
	s_andn2_b64 vcc, exec, s[10:11]
	s_cbranch_vccnz .LBB0_1229
	s_barrier
	s_branch .LBB0_1229
